# speedup vs baseline: 1.0272x; 1.0272x over previous
; DEV int tid_opaque() { int t = threadIdx.x; asm volatile("" : "+v"(t)); return t; }
; #define RAW_BARRIER() do { asm volatile("s_waitcnt lgkmcnt(0)" ::: "memory"); __builtin_amdgcn_s_barrier(); } while (0)
; #define GLDS_TILE(kt, st) do { _Pragma("unroll") for (int _i = 0; _i < NP; ++_i) GLDS_PIECE(_i, kt, st); } while (0)
;     constexpr int BROWS = 32 * NI, STAGE = 8192 + BROWS * 64, NB = BROWS / 64;
;     const int t = tid_opaque(), lane = t & 63, wid = t >> 6, wm = wid >> 1, wn = wid & 1, fr = lane & 15, fq = lane >> 4;
;     const int nk = K >> 5;
;     const int srow = wid * 16 + (lane >> 2), sch = (lane & 3) ^ ((0 - (lane >> 4)) & 3);
;     const bf16_t* ga = A + (size_t)srow * lda + sch * 8;
;     const bf16_t* gb = B + (size_t)srow * ldb + sch * 8;
;     const int rd = fr * 64 + ((fq ^ ((0 - (fr >> 2)) & 3)) << 4);
;     const int rda = (wm * 64) * 64 + rd, rdb = 8192 + (wn * 16 * NI) * 64 + rd;
;     ...
;     constexpr int NH = NI >= 4 ? NI / 2 : NI;
;     constexpr int NP = 2 + NB, IVL = (4 * NI) / NP;
;     RAW_BARRIER();
;     GLDS_TILE(0, 0);
;     GLDS_TILE(1, 1);
; DEV void resid_big(const Params& p, int l, int mt, int nt, const bf16_t* A, int K, const bf16_t* W, int gate_off, bool res_from_input, char* smem) {
;     f32x4 acc[4][8]; zero_accn<8>(acc);
;     gemm_glds<8>(A + (size_t)mt * 128 * K, K, W + (size_t)nt * 256 * K, K, K, acc, smem);
.LBB0_20:
	s_ashr_i32 s9, s20, 2
	s_and_b32 s8, s20, 7
	s_and_b32 s31, s9, -8
	s_or_b32 s21, s31, s8
	s_and_b32 s30, s19, 7
	s_mul_i32 s8, s21, 0xb0000
	s_mul_hi_i32 s9, s21, 0xb0000
	s_add_u32 s8, s12, s8
	s_addc_u32 s9, s13, s9
	s_lshl_b32 s22, s20, 5
	v_mov_b32_e32 v6, v186
	s_and_b32 s22, s22, 0x300
	s_mul_i32 s23, s22, 0x1600
	v_bfe_u32 v5, v6, 4, 2
	v_sub_u32_e32 v8, 0, v5
	s_add_u32 s28, s14, s23
	v_xor_b32_e32 v2, v6, v8
	s_addc_u32 s29, s15, 0
	v_ashrrev_i32_e32 v4, 6, v6
	v_bfe_u32 v0, v6, 2, 4
	v_lshlrev_b32_e32 v2, 4, v2
	v_lshl_or_b32 v7, v4, 4, v0
	v_and_b32_e32 v7, -2, v7
	v_mov_b64_e32 v[0:1], s[8:9]
	s_movk_i32 s34, 0x1600
	v_and_b32_e32 v32, 48, v2
	v_lshlrev_b32_e32 v9, 4, v6
	v_and_b32_e32 v9, 64, v9
	v_or_b32_e32 v32, v32, v9
	v_mov_b64_e32 v[2:3], s[28:29]
	v_mad_i64_i32 v[0:1], s[8:9], v7, s34, v[0:1]
	v_mad_i64_i32 v[2:3], s[8:9], v7, s34, v[2:3]
	v_lshl_add_u64 v[0:1], v[0:1], 0, v[32:33]
	v_lshl_add_u64 v[2:3], v[2:3], 0, v[32:33]
	v_lshl_add_u32 v32, v4, 10, 0
	v_lshrrev_b32_e32 v10, 2, v6
	v_readfirstlane_b32 s8, v32
	v_add_u32_e32 v14, 0x1000, v32
	v_sub_u32_e32 v10, 0, v10
	v_add_u32_e32 v13, 0x2000, v32
	s_mov_b32 m0, s8
	s_mov_b64 s[28:29], 0x58000
	v_readfirstlane_b32 s8, v14
	v_bitop3_b32 v10, v5, v10, 3 bitop3:0x78
	v_lshlrev_b32_e32 v12, 13, v4
	s_waitcnt lgkmcnt(0)
	s_barrier
	global_load_lds_dwordx4 v[0:1], off
	v_lshl_add_u64 v[4:5], v[0:1], 0, s[28:29]
	s_mov_b32 m0, s8
	v_readfirstlane_b32 s8, v13
	v_add_u32_e32 v13, 0x3000, v32
	global_load_lds_dwordx4 v[4:5], off
	s_mov_b32 m0, s8
	v_readfirstlane_b32 s8, v13
	global_load_lds_dwordx4 v[2:3], off
	v_lshl_add_u64 v[4:5], v[2:3], 0, s[28:29]
	s_mov_b32 m0, s8
	s_mov_b64 s[8:9], 0xb0000
	v_add_u32_e32 v13, 0x4000, v32
	global_load_lds_dwordx4 v[4:5], off
	v_lshl_add_u64 v[4:5], v[2:3], 0, s[8:9]
	v_readfirstlane_b32 s8, v13
	s_mov_b32 m0, s8
	s_mov_b64 s[8:9], 0x108000
	v_add_u32_e32 v13, 0x5000, v32
	global_load_lds_dwordx4 v[4:5], off
	v_lshl_add_u64 v[4:5], v[2:3], 0, s[8:9]
	v_readfirstlane_b32 s8, v13
	v_lshlrev_b32_e32 v9, 6, v6
	s_mov_b32 m0, s8
	v_lshlrev_b32_e32 v11, 5, v6
	global_load_lds_dwordx4 v[4:5], off
	v_and_b32_e32 v4, 0x3c0, v9
	v_lshl_or_b32 v9, v10, 4, v4
	s_movk_i32 s8, 0xf000
	v_add_u32_e32 v10, 0x6000, v32
	v_and_or_b32 v134, v11, s8, v9
	v_readfirstlane_b32 s8, v10
	v_lshl_add_u64 v[4:5], v[0:1], 0, 64
	v_lshl_add_u64 v[4:5], v[4:5], 0, 64
	s_mov_b32 m0, s8
	v_add_u32_e32 v11, 0x8000, v32
	global_load_lds_dwordx4 v[4:5], off
	v_add_u32_e32 v4, 0x7000, v32
	s_mov_b64 s[28:29], 0x58080
	v_readfirstlane_b32 s8, v4
	v_lshl_add_u64 v[0:1], v[0:1], 0, s[28:29]
	s_mov_b32 m0, s8
	v_readfirstlane_b32 s8, v11
	v_add_u32_e32 v4, 0x9000, v32
	global_load_lds_dwordx4 v[0:1], off
	v_lshl_add_u64 v[0:1], v[2:3], 0, 64
	v_lshl_add_u64 v[0:1], v[0:1], 0, 64
	s_mov_b32 m0, s8
	v_readfirstlane_b32 s8, v4
	global_load_lds_dwordx4 v[0:1], off
	v_lshl_add_u64 v[0:1], v[2:3], 0, s[28:29]
	s_mov_b32 m0, s8
	s_mov_b64 s[8:9], 0xb0080
	v_add_u32_e32 v4, 0xa000, v32
	global_load_lds_dwordx4 v[0:1], off
	v_lshl_add_u64 v[0:1], v[2:3], 0, s[8:9]
	v_readfirstlane_b32 s8, v4
	s_mov_b32 m0, s8
	s_mov_b64 s[8:9], 0x108080
	global_load_lds_dwordx4 v[0:1], off
	v_lshl_add_u64 v[0:1], v[2:3], 0, s[8:9]
	v_add_u32_e32 v2, 0xb000, v32
	s_or_b32 s28, s31, s30
	v_readfirstlane_b32 s8, v2
	s_mov_b32 m0, s8
	s_movk_i32 s8, 0x2000
	global_load_lds_dwordx4 v[0:1], off
	v_and_or_b32 v135, v12, s8, v9
	v_mad_i64_i32 v[0:1], s[8:9], v7, s34, 0
	v_mad_i64_i32 v[2:3], s[8:9], s28, v187, v[0:1]
	v_bitop3_b32 v4, v6, 3, v8 bitop3:0x48
	s_bfe_u32 s8, s17, 0x20008
	v_lshlrev_b32_e32 v4, 4, v4
	v_lshlrev_b32_e32 v5, 4, v6
	v_and_b32_e32 v5, 64, v5
	v_or_b32_e32 v4, v4, v5
	v_mad_u64_u32 v[0:1], s[8:9], s8, v188, v[0:1]
	v_readlane_b32 s2, v254, 1
	v_or_b32_e32 v0, v0, v4
	v_or_b32_e32 v2, v2, v4
	v_readlane_b32 s3, v254, 2
	v_lshl_add_u64 v[132:133], s[4:5], 0, v[0:1]
	v_lshl_add_u64 v[132:133], v[132:133], 0, 64
	v_lshl_add_u64 v[132:133], v[132:133], 0, 64
	v_mov_b32_e32 v0, 0
	s_mov_b32 s23, 0
	v_lshl_add_u64 v[130:131], s[2:3], 0, v[2:3]
	v_lshl_add_u64 v[130:131], v[130:131], 0, 64
	v_lshl_add_u64 v[130:131], v[130:131], 0, 64
	s_mov_b64 s[8:9], 0
	v_mov_b32_e32 v1, v0
	v_mov_b32_e32 v2, v0
	v_mov_b32_e32 v3, v0
	v_mov_b32_e32 v4, v0
	v_mov_b32_e32 v5, v0
	v_mov_b32_e32 v6, v0
	v_mov_b32_e32 v7, v0
	v_mov_b32_e32 v8, v0
	v_mov_b32_e32 v9, v0
	v_mov_b32_e32 v10, v0
	v_mov_b32_e32 v11, v0
	v_mov_b32_e32 v12, v0
	v_mov_b32_e32 v13, v0
	v_mov_b32_e32 v14, v0
	v_mov_b32_e32 v15, v0
	v_mov_b32_e32 v20, v0
	v_mov_b32_e32 v21, v0
	v_mov_b32_e32 v22, v0
	v_mov_b32_e32 v23, v0
	v_mov_b32_e32 v28, v0
	v_mov_b32_e32 v29, v0
	v_mov_b32_e32 v30, v0
	v_mov_b32_e32 v31, v0
	v_mov_b32_e32 v38, v0
	v_mov_b32_e32 v39, v0
	v_mov_b32_e32 v40, v0
	v_mov_b32_e32 v41, v0
	v_mov_b32_e32 v50, v0
	v_mov_b32_e32 v51, v0
	v_mov_b32_e32 v52, v0
	v_mov_b32_e32 v53, v0
	v_mov_b32_e32 v16, v0
	v_mov_b32_e32 v17, v0
	v_mov_b32_e32 v18, v0
	v_mov_b32_e32 v19, v0
	v_mov_b32_e32 v24, v0
	v_mov_b32_e32 v25, v0
	v_mov_b32_e32 v26, v0
	v_mov_b32_e32 v27, v0
	v_mov_b32_e32 v34, v0
	v_mov_b32_e32 v35, v0
	v_mov_b32_e32 v36, v0
	v_mov_b32_e32 v37, v0
	v_mov_b32_e32 v42, v0
	v_mov_b32_e32 v43, v0
	v_mov_b32_e32 v44, v0
	v_mov_b32_e32 v45, v0
	v_mov_b32_e32 v54, v0
	v_mov_b32_e32 v55, v0
	v_mov_b32_e32 v56, v0
	v_mov_b32_e32 v57, v0
	s_waitcnt vmcnt(0)
; #define RAW_BARRIER() do { asm volatile("s_waitcnt lgkmcnt(0)" ::: "memory"); __builtin_amdgcn_s_barrier(); } while (0)
; #define GLDS_TILE(kt, st) do { _Pragma("unroll") for (int _i = 0; _i < NP; ++_i) GLDS_PIECE(_i, kt, st); } while (0)
;     ...
;     constexpr int NH = NI >= 4 ? NI / 2 : NI;
;     constexpr int NP = 2 + NB, IVL = (4 * NI) / NP;
;     RAW_BARRIER();
;     GLDS_TILE(0, 0);
;     GLDS_TILE(1, 1);
;     int st = 0;
;     for (int kt = 0; kt < nk - 1; ++kt) {
;         if (NI == 8) asm volatile("s_waitcnt vmcnt(6)" ::: "memory"); else if (NI == 4) asm volatile("s_waitcnt vmcnt(4)" ::: "memory"); else asm volatile("s_waitcnt vmcnt(3)" ::: "memory");
;         RAW_BARRIER();
;         const int s2 = st >= 1 ? st - 1 : 2;
;         const bool ld = kt + 2 < nk;
;         STEP_TILE(st, ld, kt + 2, s2);
;         st = st == 2 ? 0 : st + 1;
;     }
	v_mov_b32_e32 v62, v0
	v_mov_b32_e32 v63, v0
	v_mov_b32_e32 v64, v0
	v_mov_b32_e32 v65, v0
	v_mov_b32_e32 v70, v0
	v_mov_b32_e32 v71, v0
	v_mov_b32_e32 v72, v0
	v_mov_b32_e32 v73, v0
	v_mov_b32_e32 v82, v0
	v_mov_b32_e32 v83, v0
	v_mov_b32_e32 v84, v0
	v_mov_b32_e32 v85, v0
	v_mov_b32_e32 v46, v0
	v_mov_b32_e32 v47, v0
	v_mov_b32_e32 v48, v0
	v_mov_b32_e32 v49, v0
	v_mov_b32_e32 v58, v0
	v_mov_b32_e32 v59, v0
	v_mov_b32_e32 v60, v0
	v_mov_b32_e32 v61, v0
	v_mov_b32_e32 v66, v0
	v_mov_b32_e32 v67, v0
	v_mov_b32_e32 v68, v0
	v_mov_b32_e32 v69, v0
	v_mov_b32_e32 v74, v0
	v_mov_b32_e32 v75, v0
	v_mov_b32_e32 v76, v0
	v_mov_b32_e32 v77, v0
	v_mov_b32_e32 v86, v0
	v_mov_b32_e32 v87, v0
	v_mov_b32_e32 v88, v0
	v_mov_b32_e32 v89, v0
	v_mov_b32_e32 v94, v0
	v_mov_b32_e32 v95, v0
	v_mov_b32_e32 v96, v0
	v_mov_b32_e32 v97, v0
	v_mov_b32_e32 v102, v0
	v_mov_b32_e32 v103, v0
	v_mov_b32_e32 v104, v0
	v_mov_b32_e32 v105, v0
	v_mov_b32_e32 v110, v0
	v_mov_b32_e32 v111, v0
	v_mov_b32_e32 v112, v0
	v_mov_b32_e32 v113, v0
	v_mov_b32_e32 v78, v0
	v_mov_b32_e32 v79, v0
	v_mov_b32_e32 v80, v0
	v_mov_b32_e32 v81, v0
	v_mov_b32_e32 v90, v0
	v_mov_b32_e32 v91, v0
	v_mov_b32_e32 v92, v0
	v_mov_b32_e32 v93, v0
	v_mov_b32_e32 v98, v0
	v_mov_b32_e32 v99, v0
	v_mov_b32_e32 v100, v0
	v_mov_b32_e32 v101, v0
	v_mov_b32_e32 v106, v0
	v_mov_b32_e32 v107, v0
	v_mov_b32_e32 v108, v0
	v_mov_b32_e32 v109, v0
	v_mov_b32_e32 v114, v0
	v_mov_b32_e32 v115, v0
	v_mov_b32_e32 v116, v0
	v_mov_b32_e32 v117, v0
	v_mov_b32_e32 v118, v0
	v_mov_b32_e32 v119, v0
	v_mov_b32_e32 v120, v0
	v_mov_b32_e32 v121, v0
	v_mov_b32_e32 v122, v0
	v_mov_b32_e32 v123, v0
	v_mov_b32_e32 v124, v0
	v_mov_b32_e32 v125, v0
	v_mov_b32_e32 v126, v0
	v_mov_b32_e32 v127, v0
	v_mov_b32_e32 v128, v0
	v_mov_b32_e32 v129, v0
	s_mov_b64 s[30:31], 0x3500080
.LBB0_21:
	s_mul_i32 s28, s23, 0x6000
	s_add_i32 s29, s28, 0
	s_waitcnt vmcnt(6)
	v_add_u32_e32 v148, s29, v134
	v_add_u32_e32 v155, s29, v135
	s_waitcnt lgkmcnt(0)
	s_barrier
	ds_read_b128 v[136:139], v148
	ds_read_b128 v[140:143], v148 offset:1024
	ds_read_b128 v[144:147], v148 offset:2048
	ds_read_b128 v[148:151], v148 offset:3072
	ds_read_b128 v[158:161], v155 offset:8192
	ds_read_b128 v[162:165], v155 offset:9216
	ds_read_b128 v[166:169], v155 offset:10240
	ds_read_b128 v[170:173], v155 offset:11264
	s_addk_i32 s28, 0xa000
	s_cmp_gt_i32 s23, 0
	s_setprio 1
	s_waitcnt lgkmcnt(0)
	v_mfma_f32_16x16x32_bf16 v[126:129], v[158:161], v[136:139], v[126:129]
	s_cselect_b32 s28, s28, 0xc000
	v_add_u32_e32 v157, s28, v32
	v_lshl_add_u64 v[152:153], v[132:133], 0, s[8:9]
	v_mfma_f32_16x16x32_bf16 v[110:113], v[158:161], v[140:143], v[110:113]
	v_lshl_add_u64 v[208:209], v[130:131], 0, s[8:9]
	s_mov_b64 s[28:29], 0xb52c080
	v_lshl_add_u64 v[206:207], v[152:153], 0, s[30:31]
	v_mfma_f32_16x16x32_bf16 v[82:85], v[158:161], v[144:147], v[82:85]
	v_add_u32_e32 v205, 0x2000, v157
	v_mfma_f32_16x16x32_bf16 v[50:53], v[158:161], v[148:151], v[50:53]
	v_lshl_add_u64 v[158:159], v[208:209], 0, s[28:29]
	v_mfma_f32_16x16x32_bf16 v[122:125], v[162:165], v[136:139], v[122:125]
	v_readfirstlane_b32 s28, v157
	s_mov_b32 m0, s28
	s_nop 0
	global_load_lds_dwordx4 v[158:159], off
	ds_read_b128 v[158:161], v155 offset:12288
	ds_read_b128 v[174:177], v155 offset:13312
	ds_read_b128 v[178:181], v155 offset:14336
	ds_read_b128 v[182:185], v155 offset:15360
	v_mfma_f32_16x16x32_bf16 v[102:105], v[162:165], v[140:143], v[102:105]
	v_mfma_f32_16x16x32_bf16 v[70:73], v[162:165], v[144:147], v[70:73]
	v_mfma_f32_16x16x32_bf16 v[38:41], v[162:165], v[148:151], v[38:41]
	v_mfma_f32_16x16x32_bf16 v[118:121], v[166:169], v[136:139], v[118:121]
	v_mfma_f32_16x16x32_bf16 v[94:97], v[166:169], v[140:143], v[94:97]
	v_add_u32_e32 v155, 0x1000, v157
	s_mov_b64 s[28:29], 0xb584080
	v_lshl_add_u64 v[162:163], v[208:209], 0, s[28:29]
	v_readfirstlane_b32 s28, v155
	s_mov_b32 m0, s28
	s_nop 0
	global_load_lds_dwordx4 v[162:163], off
	v_mfma_f32_16x16x32_bf16 v[62:65], v[166:169], v[144:147], v[62:65]
	v_mfma_f32_16x16x32_bf16 v[28:31], v[166:169], v[148:151], v[28:31]
	v_mfma_f32_16x16x32_bf16 v[114:117], v[170:173], v[136:139], v[114:117]
	v_mfma_f32_16x16x32_bf16 v[86:89], v[170:173], v[140:143], v[86:89]
	v_mfma_f32_16x16x32_bf16 v[54:57], v[170:173], v[144:147], v[54:57]
	v_readfirstlane_b32 s28, v205
	s_mov_b32 m0, s28
	s_nop 0
	global_load_lds_dwordx4 v[206:207], off
	v_mfma_f32_16x16x32_bf16 v[20:23], v[170:173], v[148:151], v[20:23]
	s_waitcnt lgkmcnt(0)
	v_mfma_f32_16x16x32_bf16 v[106:109], v[158:161], v[136:139], v[106:109]
	v_mfma_f32_16x16x32_bf16 v[74:77], v[158:161], v[140:143], v[74:77]
	v_mfma_f32_16x16x32_bf16 v[42:45], v[158:161], v[144:147], v[42:45]
	v_mfma_f32_16x16x32_bf16 v[12:15], v[158:161], v[148:151], v[12:15]
	v_add_u32_e32 v155, 0x3000, v157
	s_mov_b64 s[28:29], 0x3558080
	v_lshl_add_u64 v[158:159], v[152:153], 0, s[28:29]
	v_readfirstlane_b32 s28, v155
	s_mov_b32 m0, s28
	s_nop 0
	global_load_lds_dwordx4 v[158:159], off
	v_mfma_f32_16x16x32_bf16 v[98:101], v[174:177], v[136:139], v[98:101]
	v_mfma_f32_16x16x32_bf16 v[66:69], v[174:177], v[140:143], v[66:69]
	v_mfma_f32_16x16x32_bf16 v[34:37], v[174:177], v[144:147], v[34:37]
	v_mfma_f32_16x16x32_bf16 v[8:11], v[174:177], v[148:151], v[8:11]
	v_mfma_f32_16x16x32_bf16 v[90:93], v[178:181], v[136:139], v[90:93]
	v_add_u32_e32 v155, 0x4000, v157
	s_mov_b64 s[28:29], 0x35b0080
	v_lshl_add_u64 v[158:159], v[152:153], 0, s[28:29]
	v_readfirstlane_b32 s28, v155
	s_mov_b32 m0, s28
	s_nop 0
	global_load_lds_dwordx4 v[158:159], off
	v_mfma_f32_16x16x32_bf16 v[58:61], v[178:181], v[140:143], v[58:61]
	v_mfma_f32_16x16x32_bf16 v[24:27], v[178:181], v[144:147], v[24:27]
	v_mfma_f32_16x16x32_bf16 v[4:7], v[178:181], v[148:151], v[4:7]
	v_mfma_f32_16x16x32_bf16 v[78:81], v[182:185], v[136:139], v[78:81]
	v_mfma_f32_16x16x32_bf16 v[46:49], v[182:185], v[140:143], v[46:49]
	v_add_u32_e32 v138, 0x5000, v157
	s_mov_b64 s[28:29], 0x3608080
	v_lshl_add_u64 v[136:137], v[152:153], 0, s[28:29]
	v_readfirstlane_b32 s28, v138
	s_mov_b32 m0, s28
	s_nop 0
	global_load_lds_dwordx4 v[136:137], off
	v_mfma_f32_16x16x32_bf16 v[16:19], v[182:185], v[144:147], v[16:19]
	v_mfma_f32_16x16x32_bf16 v[0:3], v[182:185], v[148:151], v[0:3]
	s_setprio 0
	s_add_i32 s28, s23, 1
	s_cmp_lg_u32 s23, 2
	s_cselect_b32 s23, s28, 0
	s_add_u32 s8, s8, 0x80
	s_addc_u32 s9, s9, 0
	s_cmpk_lg_i32 s8, 0x2b00
	s_cbranch_scc1 .LBB0_21
; #define RAW_BARRIER() do { asm volatile("s_waitcnt lgkmcnt(0)" ::: "memory"); __builtin_amdgcn_s_barrier(); } while (0)
; #define GLDS_TILE(kt, st) do { _Pragma("unroll") for (int _i = 0; _i < NP; ++_i) GLDS_PIECE(_i, kt, st); } while (0)
;     ...
;     constexpr int NH = NI >= 4 ? NI / 2 : NI;
;     constexpr int NP = 2 + NB, IVL = (4 * NI) / NP;
;     RAW_BARRIER();
;     GLDS_TILE(0, 0);
;     GLDS_TILE(1, 1);
;     int st = 0;
;     for (int kt = 0; kt < nk - 1; ++kt) {
;         if (NI == 8) asm volatile("s_waitcnt vmcnt(6)" ::: "memory"); else if (NI == 4) asm volatile("s_waitcnt vmcnt(4)" ::: "memory"); else asm volatile("s_waitcnt vmcnt(3)" ::: "memory");
;         RAW_BARRIER();
;         const int s2 = st >= 1 ? st - 1 : 2;
;         const bool ld = kt + 2 < nk;
;         STEP_TILE(st, ld, kt + 2, s2);
;         st = st == 2 ? 0 : st + 1;
;     }
;     asm volatile("s_waitcnt vmcnt(0)" ::: "memory");
;     RAW_BARRIER();
;     STEP_TILE(st, false, 0, 0);
;     RAW_BARRIER();
	s_waitcnt vmcnt(6)
	v_add_u32_e32 v32, 0, v134
	v_add_u32_e32 v152, 0, v135
	s_waitcnt lgkmcnt(0)
	s_barrier
	ds_read_b128 v[130:133], v32 offset:49152
	ds_read_b128 v[136:139], v32 offset:50176
	ds_read_b128 v[140:143], v32 offset:51200
	ds_read_b128 v[144:147], v32 offset:52224
	ds_read_b128 v[148:151], v152 offset:57344
	ds_read_b128 v[158:161], v152 offset:58368
	ds_read_b128 v[162:165], v152 offset:59392
	ds_read_b128 v[166:169], v152 offset:60416
	s_setprio 1
	s_waitcnt lgkmcnt(0)
	v_mfma_f32_16x16x32_bf16 v[126:129], v[148:151], v[130:133], v[126:129]
	v_mfma_f32_16x16x32_bf16 v[110:113], v[148:151], v[136:139], v[110:113]
	v_mfma_f32_16x16x32_bf16 v[82:85], v[148:151], v[140:143], v[82:85]
	v_mfma_f32_16x16x32_bf16 v[50:53], v[148:151], v[144:147], v[50:53]
	v_mfma_f32_16x16x32_bf16 v[122:125], v[158:161], v[130:133], v[122:125]
	ds_read_b128 v[148:151], v152 offset:61440
	ds_read_b128 v[170:173], v152 offset:62464
	ds_read_b128 v[174:177], v152 offset:63488
	ds_read_b128 v[178:181], v152 offset:64512
	v_mfma_f32_16x16x32_bf16 v[102:105], v[158:161], v[136:139], v[102:105]
	v_mfma_f32_16x16x32_bf16 v[70:73], v[158:161], v[140:143], v[70:73]
	v_mfma_f32_16x16x32_bf16 v[38:41], v[158:161], v[144:147], v[38:41]
	v_mfma_f32_16x16x32_bf16 v[118:121], v[162:165], v[130:133], v[118:121]
	v_mfma_f32_16x16x32_bf16 v[158:161], v[162:165], v[136:139], v[94:97]
	v_mfma_f32_16x16x32_bf16 v[182:185], v[162:165], v[140:143], v[62:65]
	v_mfma_f32_16x16x32_bf16 v[162:165], v[162:165], v[144:147], v[28:31]
	v_mfma_f32_16x16x32_bf16 v[114:117], v[166:169], v[130:133], v[114:117]
	v_mfma_f32_16x16x32_bf16 v[206:209], v[166:169], v[136:139], v[86:89]
	v_mfma_f32_16x16x32_bf16 v[210:213], v[166:169], v[140:143], v[54:57]
	v_mfma_f32_16x16x32_bf16 v[166:169], v[166:169], v[144:147], v[20:23]
	s_waitcnt lgkmcnt(0)
	v_mfma_f32_16x16x32_bf16 v[106:109], v[148:151], v[130:133], v[106:109]
	v_mfma_f32_16x16x32_bf16 v[74:77], v[148:151], v[136:139], v[74:77]
	v_mfma_f32_16x16x32_bf16 v[42:45], v[148:151], v[140:143], v[42:45]
	v_mfma_f32_16x16x32_bf16 v[12:15], v[148:151], v[144:147], v[12:15]
	v_mfma_f32_16x16x32_bf16 v[98:101], v[170:173], v[130:133], v[98:101]
	v_mfma_f32_16x16x32_bf16 v[66:69], v[170:173], v[136:139], v[66:69]
	v_mfma_f32_16x16x32_bf16 v[34:37], v[170:173], v[140:143], v[34:37]
	v_mfma_f32_16x16x32_bf16 v[8:11], v[170:173], v[144:147], v[8:11]
	v_mfma_f32_16x16x32_bf16 v[148:151], v[174:177], v[130:133], v[90:93]
	v_mfma_f32_16x16x32_bf16 v[170:173], v[174:177], v[136:139], v[58:61]
	v_mfma_f32_16x16x32_bf16 v[214:217], v[174:177], v[140:143], v[24:27]
	v_mfma_f32_16x16x32_bf16 v[4:7], v[174:177], v[144:147], v[4:7]
	v_mfma_f32_16x16x32_bf16 v[130:133], v[178:181], v[130:133], v[78:81]
	v_mfma_f32_16x16x32_bf16 v[134:137], v[178:181], v[136:139], v[46:49]
	v_mfma_f32_16x16x32_bf16 v[138:141], v[178:181], v[140:143], v[16:19]
	v_mfma_f32_16x16x32_bf16 v[0:3], v[178:181], v[144:147], v[0:3]
	s_setprio 0
	s_waitcnt vmcnt(0)
	s_waitcnt lgkmcnt(0)
	s_barrier
	ds_read_b128 v[142:145], v32
	ds_read_b128 v[174:177], v32 offset:1024
	ds_read_b128 v[178:181], v32 offset:2048
	ds_read_b128 v[218:221], v32 offset:3072
	ds_read_b128 v[16:19], v152 offset:8192
	ds_read_b128 v[20:23], v152 offset:9216
	ds_read_b128 v[46:49], v152 offset:10240
	ds_read_b128 v[78:81], v152 offset:11264
	s_setprio 1
	s_waitcnt lgkmcnt(0)
	v_mfma_f32_16x16x32_bf16 v[126:129], v[16:19], v[142:145], v[126:129]
	v_mfma_f32_16x16x32_bf16 v[94:97], v[16:19], v[174:177], v[110:113]
	v_mfma_f32_16x16x32_bf16 v[62:65], v[16:19], v[178:181], v[82:85]
	v_mfma_f32_16x16x32_bf16 v[28:31], v[16:19], v[218:221], v[50:53]
	v_mfma_f32_16x16x32_bf16 v[122:125], v[20:23], v[142:145], v[122:125]
	ds_read_b128 v[110:113], v152 offset:12288
	ds_read_b128 v[222:225], v152 offset:13312
	ds_read_b128 v[226:229], v152 offset:14336
	ds_read_b128 v[230:233], v152 offset:15360
	v_mfma_f32_16x16x32_bf16 v[90:93], v[20:23], v[174:177], v[102:105]
	v_mfma_f32_16x16x32_bf16 v[58:61], v[20:23], v[178:181], v[70:73]
	v_mfma_f32_16x16x32_bf16 v[24:27], v[20:23], v[218:221], v[38:41]
	v_mfma_f32_16x16x32_bf16 v[118:121], v[46:49], v[142:145], v[118:121]
	v_mfma_f32_16x16x32_bf16 v[86:89], v[46:49], v[174:177], v[158:161]
	v_mfma_f32_16x16x32_bf16 v[54:57], v[46:49], v[178:181], v[182:185]
	v_mfma_f32_16x16x32_bf16 v[20:23], v[46:49], v[218:221], v[162:165]
	v_mfma_f32_16x16x32_bf16 v[114:117], v[78:81], v[142:145], v[114:117]
	v_mfma_f32_16x16x32_bf16 v[82:85], v[78:81], v[174:177], v[206:209]
	v_mfma_f32_16x16x32_bf16 v[50:53], v[78:81], v[178:181], v[210:213]
	v_mfma_f32_16x16x32_bf16 v[16:19], v[78:81], v[218:221], v[166:169]
	s_waitcnt lgkmcnt(0)
	v_mfma_f32_16x16x32_bf16 v[158:161], v[110:113], v[142:145], v[106:109]
	v_mfma_f32_16x16x32_bf16 v[78:81], v[110:113], v[174:177], v[74:77]
	v_mfma_f32_16x16x32_bf16 v[46:49], v[110:113], v[178:181], v[42:45]
	v_mfma_f32_16x16x32_bf16 v[12:15], v[110:113], v[218:221], v[12:15]
	v_mfma_f32_16x16x32_bf16 v[162:165], v[222:225], v[142:145], v[98:101]
	v_mfma_f32_16x16x32_bf16 v[74:77], v[222:225], v[174:177], v[66:69]
	v_mfma_f32_16x16x32_bf16 v[42:45], v[222:225], v[178:181], v[34:37]
	v_mfma_f32_16x16x32_bf16 v[8:11], v[222:225], v[218:221], v[8:11]
	v_mfma_f32_16x16x32_bf16 v[102:105], v[226:229], v[142:145], v[148:151]
	v_mfma_f32_16x16x32_bf16 v[70:73], v[226:229], v[174:177], v[170:173]
	v_mfma_f32_16x16x32_bf16 v[38:41], v[226:229], v[178:181], v[214:217]
	v_mfma_f32_16x16x32_bf16 v[4:7], v[226:229], v[218:221], v[4:7]
	v_mfma_f32_16x16x32_bf16 v[98:101], v[230:233], v[142:145], v[130:133]
	v_mfma_f32_16x16x32_bf16 v[66:69], v[230:233], v[174:177], v[134:137]
	v_mfma_f32_16x16x32_bf16 v[34:37], v[230:233], v[178:181], v[138:141]
	v_mfma_f32_16x16x32_bf16 v[0:3], v[230:233], v[218:221], v[0:3]
	s_setprio 0
	v_mov_b32_e32 v32, v186
	s_waitcnt lgkmcnt(0)
	s_barrier
;     __device__ __forceinline__ float* mod() const { return (float*)(ws + OFF_mod); }
; DEV int tid_opaque() { int t = threadIdx.x; asm volatile("" : "+v"(t)); return t; }
; DEV void resid_big(const Params& p, int l, int mt, int nt, const bf16_t* A, int K, const bf16_t* W, int gate_off, bool res_from_input, char* smem) {
;     ...
;     const int t = tid_opaque(), lane = t & 63, wid = t >> 6, wm = wid >> 1, wn = wid & 1, fr = lane & 15, fq = lane >> 4;
;     const int rbase = mt * 128 + wm * 64 + fr, c0 = nt * 256 + wn * 128 + fq * 4;
; #pragma unroll
;     for (int mi = 0; mi < 4; ++mi) {
;         const int row = rbase + mi * 16;
;         const float* gt = p.mod() + (size_t)(l * 9 + mod_index(row)) * 6144 + gate_off + c0;
;         const float* res = res_from_input ? xrow(p, l, row) : p.out + (size_t)row * 1024;
;         float* dst = p.out + (size_t)row * 1024;
; #pragma unroll
;         for (int ni = 0; ni < 8; ++ni) {
;             const f32x4 g4 = *(const f32x4*)(gt + ni * 16), r4 = *(const f32x4*)(res + c0 + ni * 16);
;             *(f32x4*)(dst + c0 + ni * 16) = r4 + g4 * acc[mi][ni];
;         }
;     }
	s_mov_b64 s[28:29], 0x5000
	v_ashrrev_i32_e32 v106, 1, v32
	v_and_b32_e32 v106, 0xffffffc0, v106
	v_lshl_add_u32 v112, s21, 7, v106
	v_and_or_b32 v108, v32, 15, v112
	v_lshlrev_b32_e32 v106, 1, v32
	v_lshrrev_b32_e32 v32, 2, v32
	v_and_b32_e32 v106, 0x80, v106
	v_and_b32_e32 v32, 12, v32
	v_or3_b32 v32, v106, v32, s22
	v_add_u32_e32 v106, 0xffffc000, v112
	v_lshrrev_b32_e32 v106, 4, v106
	s_movk_i32 s22, 0x3fff
	v_or_b32_e32 v106, 1, v106
	v_cmp_lt_i32_e32 vcc, s22, v108
	v_lshlrev_b32_e32 v32, 2, v32
	s_movk_i32 s21, 0x5000
	v_cndmask_b32_e32 v106, 0, v106, vcc
	v_add_u32_e32 v109, s16, v106
	v_mov_b64_e32 v[106:107], s[6:7]
	v_mad_i64_i32 v[110:111], s[8:9], v109, s33, v[106:107]
	v_lshl_add_u64 v[130:131], v[110:111], 0, v[32:33]
	v_ashrrev_i32_e32 v109, 31, v108
	v_lshl_add_u64 v[138:139], v[130:131], 0, s[28:29]
	v_lshlrev_b64 v[110:111], 12, v[108:109]
	v_add_co_u32_e32 v130, vcc, s21, v130
	v_lshl_add_u64 v[110:111], s[92:93], 0, v[110:111]
	s_nop 0
	v_addc_co_u32_e32 v131, vcc, 0, v131, vcc
	v_lshl_add_u64 v[110:111], v[110:111], 0, v[32:33]
	flat_load_dwordx4 v[130:133], v[130:131]
	s_nop 0
	flat_load_dwordx4 v[134:137], v[110:111]
	s_add_i32 s17, s17, s18
	s_waitcnt vmcnt(0) lgkmcnt(0)
	v_pk_fma_f32 v[128:129], v[128:129], v[132:133], v[136:137]
	v_pk_fma_f32 v[126:127], v[126:127], v[130:131], v[134:135]
	flat_store_dwordx4 v[110:111], v[126:129]
	flat_load_dwordx4 v[126:129], v[138:139] offset:64
	s_nop 0
	flat_load_dwordx4 v[130:133], v[110:111] offset:64
	s_waitcnt vmcnt(0) lgkmcnt(0)
	v_pk_fma_f32 v[124:125], v[124:125], v[128:129], v[132:133]
	v_pk_fma_f32 v[122:123], v[122:123], v[126:127], v[130:131]
	flat_store_dwordx4 v[110:111], v[122:125] offset:64
	flat_load_dwordx4 v[122:125], v[138:139] offset:128
	s_nop 0
	flat_load_dwordx4 v[126:129], v[110:111] offset:128
	s_waitcnt vmcnt(0) lgkmcnt(0)
	v_pk_fma_f32 v[120:121], v[120:121], v[124:125], v[128:129]
	v_pk_fma_f32 v[118:119], v[118:119], v[122:123], v[126:127]
	flat_store_dwordx4 v[110:111], v[118:121] offset:128
	flat_load_dwordx4 v[118:121], v[138:139] offset:192
	s_nop 0
	flat_load_dwordx4 v[122:125], v[110:111] offset:192
	s_waitcnt vmcnt(0) lgkmcnt(0)
	v_pk_fma_f32 v[116:117], v[116:117], v[120:121], v[124:125]
	v_pk_fma_f32 v[114:115], v[114:115], v[118:119], v[122:123]
	flat_store_dwordx4 v[110:111], v[114:117] offset:192
	flat_load_dwordx4 v[114:117], v[138:139] offset:256
	s_nop 0
	flat_load_dwordx4 v[118:121], v[110:111] offset:256
	s_waitcnt vmcnt(0) lgkmcnt(0)
	v_pk_fma_f32 v[116:117], v[160:161], v[116:117], v[120:121]
	v_pk_fma_f32 v[114:115], v[158:159], v[114:115], v[118:119]
	flat_store_dwordx4 v[110:111], v[114:117] offset:256
	flat_load_dwordx4 v[114:117], v[138:139] offset:320
	s_nop 0
	flat_load_dwordx4 v[118:121], v[110:111] offset:320
	s_waitcnt vmcnt(0) lgkmcnt(0)
	v_pk_fma_f32 v[116:117], v[164:165], v[116:117], v[120:121]
	v_pk_fma_f32 v[114:115], v[162:163], v[114:115], v[118:119]
	flat_store_dwordx4 v[110:111], v[114:117] offset:320
	flat_load_dwordx4 v[114:117], v[138:139] offset:384
	s_nop 0
	flat_load_dwordx4 v[118:121], v[110:111] offset:384
	s_waitcnt vmcnt(0) lgkmcnt(0)
	v_pk_fma_f32 v[104:105], v[104:105], v[116:117], v[120:121]
	v_pk_fma_f32 v[102:103], v[102:103], v[114:115], v[118:119]
	flat_store_dwordx4 v[110:111], v[102:105] offset:384
	flat_load_dwordx4 v[102:105], v[138:139] offset:448
	s_nop 0
	flat_load_dwordx4 v[114:117], v[110:111] offset:448
	s_waitcnt vmcnt(0) lgkmcnt(0)
	v_pk_fma_f32 v[100:101], v[100:101], v[104:105], v[116:117]
	v_pk_fma_f32 v[98:99], v[98:99], v[102:103], v[114:115]
	flat_store_dwordx4 v[110:111], v[98:101] offset:448
	s_nop 1
	v_add_u32_e32 v98, 0xffffc010, v112
	v_or_b32_e32 v100, 16, v108
	v_lshrrev_b32_e32 v98, 4, v98
	v_add_u32_e32 v98, 1, v98
	v_cmp_lt_i32_e32 vcc, s22, v100
	v_ashrrev_i32_e32 v101, 31, v100
	v_lshlrev_b64 v[100:101], 12, v[100:101]
	v_cndmask_b32_e32 v98, 0, v98, vcc
	v_add_u32_e32 v98, s16, v98
	v_mad_i64_i32 v[98:99], s[8:9], v98, s33, v[106:107]
	v_lshl_add_u64 v[102:103], v[98:99], 0, v[32:33]
	v_lshl_add_u64 v[98:99], v[102:103], 0, s[28:29]
	v_add_co_u32_e32 v102, vcc, s21, v102
	v_lshl_add_u64 v[100:101], s[92:93], 0, v[100:101]
	s_nop 0
	v_addc_co_u32_e32 v103, vcc, 0, v103, vcc
	v_lshl_add_u64 v[100:101], v[100:101], 0, v[32:33]
	flat_load_dwordx4 v[102:105], v[102:103]
	s_nop 0
	flat_load_dwordx4 v[114:117], v[100:101]
	s_waitcnt vmcnt(0) lgkmcnt(0)
	v_pk_fma_f32 v[96:97], v[96:97], v[104:105], v[116:117]
	v_pk_fma_f32 v[94:95], v[94:95], v[102:103], v[114:115]
	flat_store_dwordx4 v[100:101], v[94:97]
	flat_load_dwordx4 v[94:97], v[98:99] offset:64
	s_nop 0
	flat_load_dwordx4 v[102:105], v[100:101] offset:64
	s_waitcnt vmcnt(0) lgkmcnt(0)
	v_pk_fma_f32 v[92:93], v[92:93], v[96:97], v[104:105]
	v_pk_fma_f32 v[90:91], v[90:91], v[94:95], v[102:103]
	flat_store_dwordx4 v[100:101], v[90:93] offset:64
	flat_load_dwordx4 v[90:93], v[98:99] offset:128
	s_nop 0
	flat_load_dwordx4 v[94:97], v[100:101] offset:128
	s_waitcnt vmcnt(0) lgkmcnt(0)
	v_pk_fma_f32 v[88:89], v[88:89], v[92:93], v[96:97]
	v_pk_fma_f32 v[86:87], v[86:87], v[90:91], v[94:95]
	flat_store_dwordx4 v[100:101], v[86:89] offset:128
	flat_load_dwordx4 v[86:89], v[98:99] offset:192
	s_nop 0
	flat_load_dwordx4 v[90:93], v[100:101] offset:192
	s_waitcnt vmcnt(0) lgkmcnt(0)
	v_pk_fma_f32 v[84:85], v[84:85], v[88:89], v[92:93]
	v_pk_fma_f32 v[82:83], v[82:83], v[86:87], v[90:91]
	flat_store_dwordx4 v[100:101], v[82:85] offset:192
	flat_load_dwordx4 v[82:85], v[98:99] offset:256
	s_nop 0
	flat_load_dwordx4 v[86:89], v[100:101] offset:256
	s_waitcnt vmcnt(0) lgkmcnt(0)
;     __device__ __forceinline__ float* mod() const { return (float*)(ws + OFF_mod); }
; DEV void resid_big(const Params& p, int l, int mt, int nt, const bf16_t* A, int K, const bf16_t* W, int gate_off, bool res_from_input, char* smem) {
;     ...
;     for (int mi = 0; mi < 4; ++mi) {
;         const int row = rbase + mi * 16;
;         const float* gt = p.mod() + (size_t)(l * 9 + mod_index(row)) * 6144 + gate_off + c0;
;         const float* res = res_from_input ? xrow(p, l, row) : p.out + (size_t)row * 1024;
;         float* dst = p.out + (size_t)row * 1024;
; #pragma unroll
;         for (int ni = 0; ni < 8; ++ni) {
;             const f32x4 g4 = *(const f32x4*)(gt + ni * 16), r4 = *(const f32x4*)(res + c0 + ni * 16);
;             *(f32x4*)(dst + c0 + ni * 16) = r4 + g4 * acc[mi][ni];
;         }
;     }
	v_pk_fma_f32 v[80:81], v[80:81], v[84:85], v[88:89]
	v_pk_fma_f32 v[78:79], v[78:79], v[82:83], v[86:87]
	flat_store_dwordx4 v[100:101], v[78:81] offset:256
	flat_load_dwordx4 v[78:81], v[98:99] offset:320
	s_nop 0
	flat_load_dwordx4 v[82:85], v[100:101] offset:320
	s_waitcnt vmcnt(0) lgkmcnt(0)
	v_pk_fma_f32 v[76:77], v[76:77], v[80:81], v[84:85]
	v_pk_fma_f32 v[74:75], v[74:75], v[78:79], v[82:83]
	flat_store_dwordx4 v[100:101], v[74:77] offset:320
	flat_load_dwordx4 v[74:77], v[98:99] offset:384
	s_nop 0
	flat_load_dwordx4 v[78:81], v[100:101] offset:384
	s_waitcnt vmcnt(0) lgkmcnt(0)
	v_pk_fma_f32 v[72:73], v[72:73], v[76:77], v[80:81]
	v_pk_fma_f32 v[70:71], v[70:71], v[74:75], v[78:79]
	flat_store_dwordx4 v[100:101], v[70:73] offset:384
	flat_load_dwordx4 v[70:73], v[98:99] offset:448
	s_nop 0
	flat_load_dwordx4 v[74:77], v[100:101] offset:448
	s_waitcnt vmcnt(0) lgkmcnt(0)
	v_pk_fma_f32 v[68:69], v[68:69], v[72:73], v[76:77]
	v_pk_fma_f32 v[66:67], v[66:67], v[70:71], v[74:75]
	flat_store_dwordx4 v[100:101], v[66:69] offset:448
	s_nop 1
	v_add_u32_e32 v66, 0xffffc020, v112
	v_or_b32_e32 v68, 32, v108
	v_lshrrev_b32_e32 v66, 4, v66
	v_or_b32_e32 v66, 1, v66
	v_cmp_lt_i32_e32 vcc, s22, v68
	v_ashrrev_i32_e32 v69, 31, v68
	v_lshlrev_b64 v[68:69], 12, v[68:69]
	v_cndmask_b32_e32 v66, 0, v66, vcc
	v_add_u32_e32 v66, s16, v66
	v_mad_i64_i32 v[66:67], s[8:9], v66, s33, v[106:107]
	v_lshl_add_u64 v[70:71], v[66:67], 0, v[32:33]
	v_lshl_add_u64 v[66:67], v[70:71], 0, s[28:29]
	v_add_co_u32_e32 v70, vcc, s21, v70
	v_lshl_add_u64 v[68:69], s[92:93], 0, v[68:69]
	s_nop 0
	v_addc_co_u32_e32 v71, vcc, 0, v71, vcc
	v_lshl_add_u64 v[68:69], v[68:69], 0, v[32:33]
	flat_load_dwordx4 v[70:73], v[70:71]
	s_nop 0
	flat_load_dwordx4 v[74:77], v[68:69]
	s_waitcnt vmcnt(0) lgkmcnt(0)
	v_pk_fma_f32 v[64:65], v[64:65], v[72:73], v[76:77]
	v_pk_fma_f32 v[62:63], v[62:63], v[70:71], v[74:75]
	flat_store_dwordx4 v[68:69], v[62:65]
	flat_load_dwordx4 v[62:65], v[66:67] offset:64
	s_nop 0
	flat_load_dwordx4 v[70:73], v[68:69] offset:64
	s_waitcnt vmcnt(0) lgkmcnt(0)
	v_pk_fma_f32 v[60:61], v[60:61], v[64:65], v[72:73]
	v_pk_fma_f32 v[58:59], v[58:59], v[62:63], v[70:71]
	flat_store_dwordx4 v[68:69], v[58:61] offset:64
	flat_load_dwordx4 v[58:61], v[66:67] offset:128
	s_nop 0
	flat_load_dwordx4 v[62:65], v[68:69] offset:128
	s_waitcnt vmcnt(0) lgkmcnt(0)
	v_pk_fma_f32 v[56:57], v[56:57], v[60:61], v[64:65]
	v_pk_fma_f32 v[54:55], v[54:55], v[58:59], v[62:63]
	flat_store_dwordx4 v[68:69], v[54:57] offset:128
	flat_load_dwordx4 v[54:57], v[66:67] offset:192
	s_nop 0
	flat_load_dwordx4 v[58:61], v[68:69] offset:192
	s_waitcnt vmcnt(0) lgkmcnt(0)
	v_pk_fma_f32 v[52:53], v[52:53], v[56:57], v[60:61]
	v_pk_fma_f32 v[50:51], v[50:51], v[54:55], v[58:59]
	flat_store_dwordx4 v[68:69], v[50:53] offset:192
	flat_load_dwordx4 v[50:53], v[66:67] offset:256
	s_nop 0
	flat_load_dwordx4 v[54:57], v[68:69] offset:256
	s_waitcnt vmcnt(0) lgkmcnt(0)
	v_pk_fma_f32 v[48:49], v[48:49], v[52:53], v[56:57]
	v_pk_fma_f32 v[46:47], v[46:47], v[50:51], v[54:55]
	flat_store_dwordx4 v[68:69], v[46:49] offset:256
	flat_load_dwordx4 v[46:49], v[66:67] offset:320
	s_nop 0
	flat_load_dwordx4 v[50:53], v[68:69] offset:320
	s_waitcnt vmcnt(0) lgkmcnt(0)
	v_pk_fma_f32 v[44:45], v[44:45], v[48:49], v[52:53]
	v_pk_fma_f32 v[42:43], v[42:43], v[46:47], v[50:51]
	flat_store_dwordx4 v[68:69], v[42:45] offset:320
	flat_load_dwordx4 v[42:45], v[66:67] offset:384
	s_nop 0
	flat_load_dwordx4 v[46:49], v[68:69] offset:384
	s_waitcnt vmcnt(0) lgkmcnt(0)
;     __device__ __forceinline__ bf16_t* Wf2() const { return (bf16_t*)(ws + OFF_Wf2); }
;     __device__ __forceinline__ float* mod() const { return (float*)(ws + OFF_mod); }
;     __device__ __forceinline__ bf16_t* Act() const { return (bf16_t*)(ws + OFF_Act); }
; DEV void resid_big(const Params& p, int l, int mt, int nt, const bf16_t* A, int K, const bf16_t* W, int gate_off, bool res_from_input, char* smem) {
;     ...
;     for (int mi = 0; mi < 4; ++mi) {
;         const int row = rbase + mi * 16;
;         const float* gt = p.mod() + (size_t)(l * 9 + mod_index(row)) * 6144 + gate_off + c0;
;         const float* res = res_from_input ? xrow(p, l, row) : p.out + (size_t)row * 1024;
;         float* dst = p.out + (size_t)row * 1024;
; #pragma unroll
;         for (int ni = 0; ni < 8; ++ni) {
;             const f32x4 g4 = *(const f32x4*)(gt + ni * 16), r4 = *(const f32x4*)(res + c0 + ni * 16);
;             *(f32x4*)(dst + c0 + ni * 16) = r4 + g4 * acc[mi][ni];
;         }
;     }
; __global__ void __launch_bounds__(256, 2) fwd_kernel(Params p) {
;     ...
;                 for (int tile = bid; tile < 128 * 4; tile += nb) { const int x = tile & 7, q = tile >> 3; resid_big(pq, l, (q >> 2) * 8 + x, q & 3, pq.Act(), DFF, pq.Wf2() + (size_t)l * 1024 * DFF, 5120, false, smem); }
	v_pk_fma_f32 v[40:41], v[40:41], v[44:45], v[48:49]
	v_pk_fma_f32 v[38:39], v[38:39], v[42:43], v[46:47]
	flat_store_dwordx4 v[68:69], v[38:41] offset:384
	flat_load_dwordx4 v[38:41], v[66:67] offset:448
	s_nop 0
	flat_load_dwordx4 v[42:45], v[68:69] offset:448
	s_waitcnt vmcnt(0) lgkmcnt(0)
	v_pk_fma_f32 v[36:37], v[36:37], v[40:41], v[44:45]
	v_pk_fma_f32 v[34:35], v[34:35], v[38:39], v[42:43]
	flat_store_dwordx4 v[68:69], v[34:37] offset:448
	v_add_u32_e32 v40, 0xffffc030, v112
	s_nop 0
	v_or_b32_e32 v34, 48, v108
	v_ashrrev_i32_e32 v35, 31, v34
	v_lshlrev_b64 v[36:37], 12, v[34:35]
	v_lshrrev_b32_e32 v35, 4, v40
	v_add_u32_e32 v35, 1, v35
	v_cmp_lt_i32_e32 vcc, s22, v34
	v_lshl_add_u64 v[38:39], s[92:93], 0, v[36:37]
	s_nop 0
	v_cndmask_b32_e32 v34, 0, v35, vcc
	v_add_u32_e32 v34, s16, v34
	v_mad_i64_i32 v[34:35], s[8:9], v34, s33, v[106:107]
	v_lshl_add_u64 v[40:41], v[34:35], 0, v[32:33]
	v_lshl_add_u64 v[34:35], v[38:39], 0, v[32:33]
	v_add_co_u32_e32 v38, vcc, s21, v40
	v_lshl_add_u64 v[36:37], v[40:41], 0, s[28:29]
	s_nop 0
	v_addc_co_u32_e32 v39, vcc, 0, v41, vcc
	flat_load_dwordx4 v[38:41], v[38:39]
	s_nop 0
	flat_load_dwordx4 v[42:45], v[34:35]
	v_readlane_b32 s8, v254, 4
	s_add_i32 s20, s20, s8
	s_add_i32 s19, s19, s8
	s_cmpk_gt_i32 s20, 0x1ff
	v_readlane_b32 s9, v254, 5
	s_waitcnt vmcnt(0) lgkmcnt(0)
	v_pk_fma_f32 v[30:31], v[30:31], v[40:41], v[44:45]
	v_pk_fma_f32 v[28:29], v[28:29], v[38:39], v[42:43]
	flat_store_dwordx4 v[34:35], v[28:31]
	flat_load_dwordx4 v[28:31], v[36:37] offset:64
	s_nop 0
	flat_load_dwordx4 v[38:41], v[34:35] offset:64
	s_waitcnt vmcnt(0) lgkmcnt(0)
	v_pk_fma_f32 v[26:27], v[26:27], v[30:31], v[40:41]
	v_pk_fma_f32 v[24:25], v[24:25], v[28:29], v[38:39]
	flat_store_dwordx4 v[34:35], v[24:27] offset:64
	flat_load_dwordx4 v[24:27], v[36:37] offset:128
	s_nop 0
	flat_load_dwordx4 v[28:31], v[34:35] offset:128
	s_waitcnt vmcnt(0) lgkmcnt(0)
	v_pk_fma_f32 v[22:23], v[22:23], v[26:27], v[30:31]
	v_pk_fma_f32 v[20:21], v[20:21], v[24:25], v[28:29]
	flat_store_dwordx4 v[34:35], v[20:23] offset:128
	flat_load_dwordx4 v[20:23], v[36:37] offset:192
	s_nop 0
	flat_load_dwordx4 v[24:27], v[34:35] offset:192
	s_waitcnt vmcnt(0) lgkmcnt(0)
	v_pk_fma_f32 v[18:19], v[18:19], v[22:23], v[26:27]
	v_pk_fma_f32 v[16:17], v[16:17], v[20:21], v[24:25]
	flat_store_dwordx4 v[34:35], v[16:19] offset:192
	flat_load_dwordx4 v[16:19], v[36:37] offset:256
	s_nop 0
	flat_load_dwordx4 v[20:23], v[34:35] offset:256
	s_waitcnt vmcnt(0) lgkmcnt(0)
	v_pk_fma_f32 v[14:15], v[14:15], v[18:19], v[22:23]
	v_pk_fma_f32 v[12:13], v[12:13], v[16:17], v[20:21]
	flat_store_dwordx4 v[34:35], v[12:15] offset:256
	flat_load_dwordx4 v[12:15], v[36:37] offset:320
	s_nop 0
	flat_load_dwordx4 v[16:19], v[34:35] offset:320
	s_waitcnt vmcnt(0) lgkmcnt(0)
	v_pk_fma_f32 v[10:11], v[10:11], v[14:15], v[18:19]
	v_pk_fma_f32 v[8:9], v[8:9], v[12:13], v[16:17]
	flat_store_dwordx4 v[34:35], v[8:11] offset:320
	flat_load_dwordx4 v[8:11], v[36:37] offset:384
	s_nop 0
	flat_load_dwordx4 v[12:15], v[34:35] offset:384
	s_waitcnt vmcnt(0) lgkmcnt(0)
	v_pk_fma_f32 v[6:7], v[6:7], v[10:11], v[14:15]
	v_pk_fma_f32 v[4:5], v[4:5], v[8:9], v[12:13]
	flat_store_dwordx4 v[34:35], v[4:7] offset:384
	flat_load_dwordx4 v[4:7], v[36:37] offset:448
	s_nop 0
	flat_load_dwordx4 v[8:11], v[34:35] offset:448
	s_waitcnt vmcnt(0) lgkmcnt(0)
	v_pk_fma_f32 v[2:3], v[2:3], v[6:7], v[10:11]
	v_pk_fma_f32 v[0:1], v[0:1], v[4:5], v[8:9]
	flat_store_dwordx4 v[34:35], v[0:3] offset:448
	s_cbranch_scc0 .LBB0_20

; DEV int tid_opaque() { int t = threadIdx.x; asm volatile("" : "+v"(t)); return t; }
; #define RAW_BARRIER() do { asm volatile("s_waitcnt lgkmcnt(0)" ::: "memory"); __builtin_amdgcn_s_barrier(); } while (0)
; #define GLDS_TILE(kt, st) do { _Pragma("unroll") for (int _i = 0; _i < NP; ++_i) GLDS_PIECE(_i, kt, st); } while (0)
;     constexpr int BROWS = 32 * NI, STAGE = 8192 + BROWS * 64, NB = BROWS / 64;
;     const int t = tid_opaque(), lane = t & 63, wid = t >> 6, wm = wid >> 1, wn = wid & 1, fr = lane & 15, fq = lane >> 4;
;     const int nk = K >> 5;
;     const int srow = wid * 16 + (lane >> 2), sch = (lane & 3) ^ ((0 - (lane >> 4)) & 3);
;     const bf16_t* ga = A + (size_t)srow * lda + sch * 8;
;     const bf16_t* gb = B + (size_t)srow * ldb + sch * 8;
;     const int rd = fr * 64 + ((fq ^ ((0 - (fr >> 2)) & 3)) << 4);
;     const int rda = (wm * 64) * 64 + rd, rdb = 8192 + (wn * 16 * NI) * 64 + rd;
;     ...
;     constexpr int NH = NI >= 4 ? NI / 2 : NI;
;     constexpr int NP = 2 + NB, IVL = (4 * NI) / NP;
;     RAW_BARRIER();
;     GLDS_TILE(0, 0);
;     GLDS_TILE(1, 1);
;     int st = 0;
;     for (int kt = 0; kt < nk - 1; ++kt) {
;         if (NI == 8) asm volatile("s_waitcnt vmcnt(6)" ::: "memory"); else if (NI == 4) asm volatile("s_waitcnt vmcnt(4)" ::: "memory"); else asm volatile("s_waitcnt vmcnt(3)" ::: "memory");
;         RAW_BARRIER();
;         const int s2 = st >= 1 ? st - 1 : 2;
;         const bool ld = kt + 2 < nk;
;         STEP_TILE(st, ld, kt + 2, s2);
;         st = st == 2 ? 0 : st + 1;
;     }
; DEV void resid_small(const Params& p, int l, int unit, const bf16_t* A, int K, const bf16_t* W, int gate_off, char* smem) {
;     const int nt = unit >> 2, kq = unit & 3, Kq = K >> 2;
;     f32x4 acc[4][2]; zero_accn<2>(acc);
;     gemm_glds<2>(A + (size_t)(MT - 1) * 128 * K + kq * Kq, K, W + (size_t)nt * 64 * K + kq * Kq, K, Kq, acc, smem);
.LBB0_25:
	s_and_b32 s10, s17, 3
	s_and_b32 s19, s18, 3
	s_mulk_i32 s10, 0xb00
	s_ashr_i32 s20, s18, 2
	s_mul_i32 s21, s19, 0xb00
	v_mov_b32_e32 v32, s10
	s_add_u32 s10, s14, s21
	s_addc_u32 s11, s15, 0
	s_mul_i32 s23, s20, 0x58000
	s_mul_hi_i32 s22, s20, 0x58000
	s_add_u32 s23, s12, s23
	v_mov_b32_e32 v6, v186
	s_addc_u32 s28, s13, s22
	s_add_u32 s22, s23, s21
	v_bfe_u32 v8, v6, 4, 2
	v_sub_u32_e32 v10, 0, v8
	s_addc_u32 s23, s28, 0
	v_ashrrev_i32_e32 v7, 6, v6
	v_bfe_u32 v0, v6, 2, 4
	v_xor_b32_e32 v2, v6, v10
	v_lshl_or_b32 v9, v7, 4, v0
	v_and_b32_e32 v9, -2, v9
	v_mov_b64_e32 v[0:1], s[10:11]
	s_movk_i32 s28, 0x1600
	v_lshlrev_b32_e32 v2, 4, v2
	v_mov_b64_e32 v[4:5], s[22:23]
	v_mad_i64_i32 v[0:1], s[10:11], v9, s28, v[0:1]
	v_and_b32_e32 v2, 48, v2
	v_lshlrev_b32_e32 v3, 4, v6
	v_and_b32_e32 v3, 64, v3
	v_or_b32_e32 v2, v2, v3
	v_mov_b32_e32 v3, v33
	v_mad_i64_i32 v[4:5], s[10:11], v9, s28, v[4:5]
	v_lshl_add_u64 v[0:1], v[0:1], 0, v[2:3]
	v_lshl_add_u64 v[2:3], v[4:5], 0, v[2:3]
	v_lshrrev_b32_e32 v5, 2, v6
	v_lshl_add_u32 v38, v7, 10, 0
	v_lshlrev_b32_e32 v4, 6, v6
	v_sub_u32_e32 v5, 0, v5
	v_readfirstlane_b32 s10, v38
	v_and_b32_e32 v4, 0x3c0, v4
	v_bitop3_b32 v5, v8, v5, 3 bitop3:0x78
	s_mov_b32 m0, s10
	s_mov_b64 s[10:11], 0x58000
	v_add_u32_e32 v13, 0x1000, v38
	v_lshl_or_b32 v8, v5, 4, v4
	v_lshlrev_b32_e32 v12, 11, v7
	v_add_u32_e32 v7, 0x2000, v38
	v_lshl_add_u64 v[4:5], v[0:1], 0, s[10:11]
	v_readfirstlane_b32 s10, v13
	s_waitcnt lgkmcnt(0)
	s_barrier
	global_load_lds_dwordx4 v[0:1], off
	s_mov_b32 m0, s10
	v_readfirstlane_b32 s10, v7
	v_lshlrev_b32_e32 v11, 5, v6
	global_load_lds_dwordx4 v[4:5], off
	s_mov_b32 m0, s10
	s_movk_i32 s10, 0xf000
	v_add_u32_e32 v7, 0x3000, v38
	v_and_or_b32 v39, v11, s10, v8
	v_readfirstlane_b32 s10, v7
	global_load_lds_dwordx4 v[2:3], off
	v_lshl_add_u64 v[4:5], v[0:1], 0, 64
	v_lshl_add_u64 v[4:5], v[4:5], 0, 64
	s_mov_b32 m0, s10
	s_mov_b64 s[10:11], 0x58080
	global_load_lds_dwordx4 v[4:5], off
	v_add_u32_e32 v4, 0x4000, v38
	v_add_u32_e32 v11, 0x5000, v38
	v_lshl_add_u64 v[0:1], v[0:1], 0, s[10:11]
	v_readfirstlane_b32 s10, v4
	s_mov_b32 m0, s10
	v_readfirstlane_b32 s10, v11
	v_lshl_add_u64 v[2:3], v[2:3], 0, 64
	v_lshl_add_u64 v[2:3], v[2:3], 0, 64
	global_load_lds_dwordx4 v[0:1], off
	s_mov_b32 m0, s10
	s_movk_i32 s10, 0x800
	global_load_lds_dwordx4 v[2:3], off
	v_bitop3_b32 v2, v6, 3, v10 bitop3:0x48
	v_and_or_b32 v40, v12, s10, v8
	v_mad_i64_i32 v[0:1], s[10:11], v9, s28, v[32:33]
	v_lshlrev_b32_e32 v4, 4, v2
	v_lshlrev_b32_e32 v5, 4, v6
	v_and_b32_e32 v5, 64, v5
	v_or_b32_e32 v4, v4, v5
	v_or_b32_e32 v2, v0, v4
	v_mov_b32_e32 v3, v1
	v_mad_i64_i32 v[0:1], s[10:11], s20, v192, v[0:1]
	v_readlane_b32 s2, v254, 1
	v_or_b32_e32 v0, v0, v4
	v_readlane_b32 s3, v254, 2
	v_lshl_add_u64 v[36:37], s[4:5], 0, v[0:1]
	v_lshl_add_u64 v[36:37], v[36:37], 0, 64
	v_lshl_add_u64 v[36:37], v[36:37], 0, 64
	v_mov_b32_e32 v0, 0
	s_mov_b32 s21, 0
	v_lshl_add_u64 v[34:35], s[2:3], 0, v[2:3]
	v_lshl_add_u64 v[34:35], v[34:35], 0, 64
	v_lshl_add_u64 v[34:35], v[34:35], 0, 64
	s_mov_b64 s[10:11], 0
	v_mov_b32_e32 v1, v0
	v_mov_b32_e32 v2, v0
	v_mov_b32_e32 v3, v0
	v_mov_b32_e32 v8, v0
	v_mov_b32_e32 v9, v0
	v_mov_b32_e32 v10, v0
	v_mov_b32_e32 v11, v0
	v_mov_b32_e32 v4, v0
	v_mov_b32_e32 v5, v0
	v_mov_b32_e32 v6, v0
	v_mov_b32_e32 v7, v0
	v_mov_b32_e32 v16, v0
	v_mov_b32_e32 v17, v0
	v_mov_b32_e32 v18, v0
	v_mov_b32_e32 v19, v0
	v_mov_b32_e32 v12, v0
	v_mov_b32_e32 v13, v0
	v_mov_b32_e32 v14, v0
	v_mov_b32_e32 v15, v0
	v_mov_b32_e32 v24, v0
	v_mov_b32_e32 v25, v0
	v_mov_b32_e32 v26, v0
	v_mov_b32_e32 v27, v0
	v_mov_b32_e32 v20, v0
	v_mov_b32_e32 v21, v0
	v_mov_b32_e32 v22, v0
	v_mov_b32_e32 v23, v0
	v_mov_b32_e32 v28, v0
	v_mov_b32_e32 v29, v0
	v_mov_b32_e32 v30, v0
	v_mov_b32_e32 v31, v0
	s_mov_b64 s[28:29], 0x3500080
.LBB0_26:
	s_mul_i32 s22, s21, 0x3000
	s_add_i32 s23, s22, 0
	s_waitcnt vmcnt(3)
	v_add_u32_e32 v32, s23, v39
	s_waitcnt lgkmcnt(0)
	s_barrier
	ds_read_b128 v[42:45], v32
	ds_read_b128 v[46:49], v32 offset:1024
	ds_read_b128 v[50:53], v32 offset:2048
	ds_read_b128 v[54:57], v32 offset:3072
	v_add_u32_e32 v32, s23, v40
	ds_read_b128 v[58:61], v32 offset:8192
	s_waitcnt vmcnt(0)
	ds_read_b128 v[62:65], v32 offset:9216
	s_addk_i32 s22, 0xd000
	s_cmp_gt_i32 s21, 0
	s_setprio 1
	s_waitcnt lgkmcnt(0)
	v_mfma_f32_16x16x32_bf16 v[28:31], v[58:61], v[42:45], v[28:31]
	s_cselect_b32 s22, s22, 0x6000
	v_add_u32_e32 v32, s22, v38
	v_lshl_add_u64 v[66:67], v[36:37], 0, s[10:11]
	v_mfma_f32_16x16x32_bf16 v[24:27], v[58:61], v[46:49], v[24:27]
	v_lshl_add_u64 v[70:71], v[34:35], 0, s[10:11]
	s_mov_b64 s[22:23], 0x10d2c080
	v_lshl_add_u64 v[68:69], v[66:67], 0, s[28:29]
	v_add_u32_e32 v41, 0x2000, v32
	v_lshl_add_u64 v[72:73], v[70:71], 0, s[22:23]
	v_readfirstlane_b32 s22, v32
	s_mov_b32 m0, s22
	s_nop 0
	global_load_lds_dwordx4 v[72:73], off
	v_mfma_f32_16x16x32_bf16 v[16:19], v[58:61], v[50:53], v[16:19]
	v_mfma_f32_16x16x32_bf16 v[8:11], v[58:61], v[54:57], v[8:11]
	s_mov_b64 s[22:23], 0x10d84080
	v_add_u32_e32 v32, 0x1000, v32
	v_lshl_add_u64 v[58:59], v[70:71], 0, s[22:23]
	v_readfirstlane_b32 s22, v32
	s_mov_b32 m0, s22
	s_nop 0
	global_load_lds_dwordx4 v[58:59], off
	v_mfma_f32_16x16x32_bf16 v[20:23], v[62:65], v[42:45], v[20:23]
	v_mfma_f32_16x16x32_bf16 v[12:15], v[62:65], v[46:49], v[12:15]
	v_readfirstlane_b32 s22, v41
	s_mov_b32 m0, s22
	s_nop 0
	global_load_lds_dwordx4 v[68:69], off
	v_mfma_f32_16x16x32_bf16 v[4:7], v[62:65], v[50:53], v[4:7]
	v_mfma_f32_16x16x32_bf16 v[0:3], v[62:65], v[54:57], v[0:3]
	s_setprio 0
	s_add_i32 s22, s21, 1
	s_cmp_lg_u32 s21, 2
	s_cselect_b32 s21, s22, 0
	s_mul_i32 s22, s21, 0x3000
	s_add_i32 s23, s22, 0
	s_waitcnt vmcnt(3)
	v_add_u32_e32 v32, s23, v39
	s_waitcnt lgkmcnt(0)
	s_barrier
; #define RAW_BARRIER() do { asm volatile("s_waitcnt lgkmcnt(0)" ::: "memory"); __builtin_amdgcn_s_barrier(); } while (0)
; #define GLDS_TILE(kt, st) do { _Pragma("unroll") for (int _i = 0; _i < NP; ++_i) GLDS_PIECE(_i, kt, st); } while (0)
;     ...
;     constexpr int NH = NI >= 4 ? NI / 2 : NI;
;     constexpr int NP = 2 + NB, IVL = (4 * NI) / NP;
;     RAW_BARRIER();
;     GLDS_TILE(0, 0);
;     GLDS_TILE(1, 1);
;     int st = 0;
;     for (int kt = 0; kt < nk - 1; ++kt) {
;         if (NI == 8) asm volatile("s_waitcnt vmcnt(6)" ::: "memory"); else if (NI == 4) asm volatile("s_waitcnt vmcnt(4)" ::: "memory"); else asm volatile("s_waitcnt vmcnt(3)" ::: "memory");
;         RAW_BARRIER();
;         const int s2 = st >= 1 ? st - 1 : 2;
;         const bool ld = kt + 2 < nk;
;         STEP_TILE(st, ld, kt + 2, s2);
;         st = st == 2 ? 0 : st + 1;
;     }
;     asm volatile("s_waitcnt vmcnt(0)" ::: "memory");
;     RAW_BARRIER();
;     STEP_TILE(st, false, 0, 0);
;     RAW_BARRIER();
	ds_read_b128 v[42:45], v32
	ds_read_b128 v[46:49], v32 offset:1024
	ds_read_b128 v[50:53], v32 offset:2048
	ds_read_b128 v[54:57], v32 offset:3072
	v_add_u32_e32 v32, s23, v40
	ds_read_b128 v[58:61], v32 offset:8192
	ds_read_b128 v[62:65], v32 offset:9216
	s_addk_i32 s22, 0xd000
	s_cmp_gt_i32 s21, 0
	s_setprio 1
	s_waitcnt lgkmcnt(0)
	v_mfma_f32_16x16x32_bf16 v[28:31], v[58:61], v[42:45], v[28:31]
	s_cselect_b32 s22, s22, 0x6000
	v_add_u32_e32 v32, s22, v38
	s_mov_b64 s[22:23], 0x3500100
	v_mfma_f32_16x16x32_bf16 v[24:27], v[58:61], v[46:49], v[24:27]
	v_lshl_add_u64 v[66:67], v[66:67], 0, s[22:23]
	s_mov_b64 s[22:23], 0x10d2c100
	v_add_u32_e32 v41, 0x2000, v32
	v_lshl_add_u64 v[68:69], v[70:71], 0, s[22:23]
	v_readfirstlane_b32 s22, v32
	s_mov_b32 m0, s22
	s_nop 0
	global_load_lds_dwordx4 v[68:69], off
	v_mfma_f32_16x16x32_bf16 v[16:19], v[58:61], v[50:53], v[16:19]
	v_mfma_f32_16x16x32_bf16 v[8:11], v[58:61], v[54:57], v[8:11]
	s_mov_b64 s[22:23], 0x10d84100
	v_add_u32_e32 v32, 0x1000, v32
	v_lshl_add_u64 v[58:59], v[70:71], 0, s[22:23]
	v_readfirstlane_b32 s22, v32
	s_mov_b32 m0, s22
	s_nop 0
	global_load_lds_dwordx4 v[58:59], off
	v_mfma_f32_16x16x32_bf16 v[20:23], v[62:65], v[42:45], v[20:23]
	v_mfma_f32_16x16x32_bf16 v[12:15], v[62:65], v[46:49], v[12:15]
	v_readfirstlane_b32 s22, v41
	s_mov_b32 m0, s22
	s_nop 0
	global_load_lds_dwordx4 v[66:67], off
	v_mfma_f32_16x16x32_bf16 v[4:7], v[62:65], v[50:53], v[4:7]
	v_mfma_f32_16x16x32_bf16 v[0:3], v[62:65], v[54:57], v[0:3]
	s_setprio 0
	s_add_i32 s22, s21, 1
	s_cmp_lg_u32 s21, 2
	s_cselect_b32 s21, s22, 0
	s_add_u32 s10, s10, 0x100
	s_addc_u32 s11, s11, 0
	s_cmpk_lg_i32 s10, 0xa00
	s_cbranch_scc1 .LBB0_26
	s_waitcnt vmcnt(3)
	v_add_u32_e32 v32, 0, v39
	s_waitcnt lgkmcnt(0)
	s_barrier
	ds_read_b128 v[34:37], v32 offset:24576
	ds_read_b128 v[42:45], v32 offset:25600
	ds_read_b128 v[46:49], v32 offset:26624
	ds_read_b128 v[50:53], v32 offset:27648
	v_add_u32_e32 v58, 0, v40
	ds_read_b128 v[38:41], v58 offset:32768
	ds_read_b128 v[54:57], v58 offset:33792
	s_setprio 1
	s_waitcnt lgkmcnt(0)
	v_mfma_f32_16x16x32_bf16 v[28:31], v[38:41], v[34:37], v[28:31]
	v_mfma_f32_16x16x32_bf16 v[24:27], v[38:41], v[42:45], v[24:27]
	v_mfma_f32_16x16x32_bf16 v[16:19], v[38:41], v[46:49], v[16:19]
	v_mfma_f32_16x16x32_bf16 v[8:11], v[38:41], v[50:53], v[8:11]
	v_mfma_f32_16x16x32_bf16 v[20:23], v[54:57], v[34:37], v[20:23]
	v_mfma_f32_16x16x32_bf16 v[34:37], v[54:57], v[42:45], v[12:15]
	v_mfma_f32_16x16x32_bf16 v[38:41], v[54:57], v[46:49], v[4:7]
	v_mfma_f32_16x16x32_bf16 v[0:3], v[54:57], v[50:53], v[0:3]
	s_setprio 0
	s_waitcnt vmcnt(0)
	s_waitcnt lgkmcnt(0)
	s_barrier
	ds_read_b128 v[42:45], v32
	ds_read_b128 v[46:49], v32 offset:1024
	ds_read_b128 v[50:53], v32 offset:2048
	ds_read_b128 v[54:57], v32 offset:3072
	ds_read_b128 v[4:7], v58 offset:8192
	ds_read_b128 v[58:61], v58 offset:9216
	s_setprio 1
	s_waitcnt lgkmcnt(0)
	v_mfma_f32_16x16x32_bf16 v[28:31], v[4:7], v[42:45], v[28:31]
	v_mfma_f32_16x16x32_bf16 v[24:27], v[4:7], v[46:49], v[24:27]
	v_mfma_f32_16x16x32_bf16 v[12:15], v[4:7], v[50:53], v[16:19]
	v_mfma_f32_16x16x32_bf16 v[4:7], v[4:7], v[54:57], v[8:11]
	v_mfma_f32_16x16x32_bf16 v[42:45], v[58:61], v[42:45], v[20:23]
	v_mfma_f32_16x16x32_bf16 v[34:37], v[58:61], v[46:49], v[34:37]
	v_mfma_f32_16x16x32_bf16 v[8:11], v[58:61], v[50:53], v[38:41]
	v_mfma_f32_16x16x32_bf16 v[0:3], v[58:61], v[54:57], v[0:3]
	s_setprio 0
	v_mov_b32_e32 v17, v186
	s_waitcnt lgkmcnt(0)
	s_barrier
;     __device__ __forceinline__ float* mod() const { return (float*)(ws + OFF_mod); }
; DEV int tid_opaque() { int t = threadIdx.x; asm volatile("" : "+v"(t)); return t; }
; DEV void resid_small(const Params& p, int l, int unit, const bf16_t* A, int K, const bf16_t* W, int gate_off, char* smem) {
;     ...
;     const int t = tid_opaque(), lane = t & 63, wid = t >> 6, wm = wid >> 1, wn = wid & 1, fr = lane & 15, fq = lane >> 4;
;     const int rbase = (MT - 1) * 128 + wm * 64 + fr, c0 = nt * 64 + wn * 32 + fq * 4;
; #pragma unroll
;     for (int mi = 0; mi < 4; ++mi) {
;         const int row = rbase + mi * 16;
;         const float* gt = p.mod() + (size_t)(l * 9 + mod_index(row)) * 6144 + gate_off + c0;
;         float* dst = (float*)(p.ws + OFF_part) + ((size_t)kq * 128 + (row - SEQ)) * 1024 + c0;
; #pragma unroll
;         for (int ni = 0; ni < 2; ++ni) {
;             const f32x4 g4 = *(const f32x4*)(gt + ni * 16);
;             *(f32x4*)(dst + ni * 16) = g4 * acc[mi][ni];
;         }
;     }
; }
	s_lshl_b32 s10, s20, 6
	v_ashrrev_i32_e32 v16, 1, v17
	v_and_b32_e32 v20, 0xffffffc0, v16
	v_and_or_b32 v16, v17, 15, v20
	v_lshrrev_b32_e32 v18, 1, v17
	v_lshrrev_b32_e32 v17, 2, v17
	v_and_b32_e32 v18, 32, v18
	v_and_b32_e32 v17, 12, v17
	v_add_u32_e32 v21, 0x4000, v16
	v_or3_b32 v18, v18, s10, v17
	v_lshrrev_b32_e32 v17, 4, v20
	s_movk_i32 s20, 0x3fff
	v_or_b32_e32 v17, 1, v17
	v_cmp_lt_i32_e32 vcc, s20, v21
	v_ashrrev_i32_e32 v19, 31, v18
	v_readlane_b32 s22, v252, 27
	v_cndmask_b32_e32 v17, 0, v17, vcc
	v_add_u32_e32 v17, s16, v17
	v_mov_b64_e32 v[20:21], s[6:7]
	v_readlane_b32 s23, v252, 28
	s_lshl_b32 s22, s19, 7
	v_mad_i64_i32 v[22:23], s[10:11], v17, s33, v[20:21]
	v_lshlrev_b64 v[18:19], 2, v[18:19]
	v_ashrrev_i32_e32 v17, 31, v16
	v_lshl_add_u64 v[22:23], v[22:23], 0, v[18:19]
	s_mov_b64 s[28:29], 0x5000
	v_lshl_add_u64 v[38:39], v[16:17], 0, s[22:23]
	s_movk_i32 s19, 0x5000
	v_lshl_add_u64 v[46:47], v[22:23], 0, s[28:29]
	v_lshlrev_b64 v[38:39], 12, v[38:39]
	v_add_co_u32_e32 v22, vcc, s19, v22
	v_lshl_add_u64 v[38:39], s[8:9], 0, v[38:39]
	s_nop 0
	v_addc_co_u32_e32 v23, vcc, 0, v23, vcc
	v_lshl_add_u64 v[48:49], v[38:39], 0, v[18:19]
	flat_load_dwordx4 v[38:41], v[22:23]
	v_or_b32_e32 v22, 16, v16
	v_add_u32_e32 v17, 0x4010, v16
	v_lshrrev_b32_e32 v23, 4, v22
	v_add_u32_e32 v23, 1, v23
	v_cmp_lt_i32_e32 vcc, s20, v17
	s_waitcnt vmcnt(0) lgkmcnt(0)
	v_pk_mul_f32 v[30:31], v[30:31], v[40:41]
	v_pk_mul_f32 v[28:29], v[28:29], v[38:39]
	flat_store_dwordx4 v[48:49], v[28:31]
	flat_load_dwordx4 v[28:31], v[46:47] offset:64
	v_cndmask_b32_e32 v17, 0, v23, vcc
	v_ashrrev_i32_e32 v23, 31, v22
	v_add_u32_e32 v17, s16, v17
	v_lshl_add_u64 v[22:23], v[22:23], 0, s[22:23]
	v_lshlrev_b64 v[22:23], 12, v[22:23]
	v_lshl_add_u64 v[22:23], s[8:9], 0, v[22:23]
	v_lshl_add_u64 v[40:41], v[22:23], 0, v[18:19]
	s_waitcnt vmcnt(0) lgkmcnt(0)
	v_pk_mul_f32 v[30:31], v[44:45], v[30:31]
	v_pk_mul_f32 v[28:29], v[42:43], v[28:29]
	flat_store_dwordx4 v[48:49], v[28:31] offset:64
	s_nop 1
	v_mad_i64_i32 v[28:29], s[10:11], v17, s33, v[20:21]
	v_lshl_add_u64 v[28:29], v[28:29], 0, v[18:19]
	v_add_co_u32_e32 v22, vcc, s19, v28
	v_lshl_add_u64 v[38:39], v[28:29], 0, s[28:29]
	s_nop 0
	v_addc_co_u32_e32 v23, vcc, 0, v29, vcc
	flat_load_dwordx4 v[28:31], v[22:23]
	v_add_u32_e32 v17, 0x4020, v16
	v_cmp_lt_i32_e32 vcc, s20, v17
	s_waitcnt vmcnt(0) lgkmcnt(0)
	v_pk_mul_f32 v[26:27], v[26:27], v[30:31]
	v_pk_mul_f32 v[24:25], v[24:25], v[28:29]
	flat_store_dwordx4 v[40:41], v[24:27]
	flat_load_dwordx4 v[22:25], v[38:39] offset:64
	s_waitcnt vmcnt(0) lgkmcnt(0)
	v_pk_mul_f32 v[22:23], v[34:35], v[22:23]
	v_pk_mul_f32 v[24:25], v[36:37], v[24:25]
	flat_store_dwordx4 v[40:41], v[22:25] offset:64
	s_nop 1
	v_or_b32_e32 v22, 32, v16
	v_lshrrev_b32_e32 v23, 4, v22
	v_or_b32_e32 v23, 1, v23
	v_cndmask_b32_e32 v17, 0, v23, vcc
	v_ashrrev_i32_e32 v23, 31, v22
	v_add_u32_e32 v17, s16, v17
	v_lshl_add_u64 v[22:23], v[22:23], 0, s[22:23]
	v_mad_i64_i32 v[24:25], s[10:11], v17, s33, v[20:21]
	v_lshlrev_b64 v[22:23], 12, v[22:23]
	v_lshl_add_u64 v[24:25], v[24:25], 0, v[18:19]
	v_lshl_add_u64 v[22:23], s[8:9], 0, v[22:23]
	v_lshl_add_u64 v[28:29], v[22:23], 0, v[18:19]
	v_add_co_u32_e32 v22, vcc, s19, v24
	v_lshl_add_u64 v[26:27], v[24:25], 0, s[28:29]
	s_nop 0
	v_addc_co_u32_e32 v23, vcc, 0, v25, vcc
	flat_load_dwordx4 v[22:25], v[22:23]
	s_waitcnt vmcnt(0) lgkmcnt(0)
	v_pk_mul_f32 v[14:15], v[14:15], v[24:25]
	v_pk_mul_f32 v[12:13], v[12:13], v[22:23]
	flat_store_dwordx4 v[28:29], v[12:15]
	flat_load_dwordx4 v[12:15], v[26:27] offset:64
	s_waitcnt vmcnt(0) lgkmcnt(0)
	v_pk_mul_f32 v[10:11], v[10:11], v[14:15]
	v_pk_mul_f32 v[8:9], v[8:9], v[12:13]
	flat_store_dwordx4 v[28:29], v[8:11] offset:64
	s_nop 1
	v_or_b32_e32 v8, 48, v16
	v_add_u32_e32 v9, 0x4030, v16
	v_lshrrev_b32_e32 v10, 4, v8
	v_add_u32_e32 v10, 1, v10
	v_cmp_lt_i32_e32 vcc, s20, v9
	s_nop 1
	v_cndmask_b32_e32 v9, 0, v10, vcc
	v_add_u32_e32 v9, s16, v9
	v_mad_i64_i32 v[10:11], s[10:11], v9, s33, v[20:21]
	v_ashrrev_i32_e32 v9, 31, v8
	v_lshl_add_u64 v[8:9], v[8:9], 0, s[22:23]
	v_lshlrev_b64 v[8:9], 12, v[8:9]
	v_lshl_add_u64 v[10:11], v[10:11], 0, v[18:19]
	v_lshl_add_u64 v[8:9], s[8:9], 0, v[8:9]
	v_lshl_add_u64 v[14:15], v[8:9], 0, v[18:19]
	v_add_co_u32_e32 v8, vcc, s19, v10
	v_lshl_add_u64 v[12:13], v[10:11], 0, s[28:29]
	s_nop 0
	v_addc_co_u32_e32 v9, vcc, 0, v11, vcc
	flat_load_dwordx4 v[8:11], v[8:9]
	s_mov_b32 s11, s23
	v_writelane_b32 v252, s10, 27
	s_waitcnt vmcnt(0) lgkmcnt(0)
	v_pk_mul_f32 v[6:7], v[6:7], v[10:11]
	v_pk_mul_f32 v[4:5], v[4:5], v[8:9]
	flat_store_dwordx4 v[14:15], v[4:7]
	flat_load_dwordx4 v[4:7], v[12:13] offset:64
	v_writelane_b32 v252, s11, 28
	v_readlane_b32 s10, v254, 4
	s_add_i32 s18, s18, s10
	s_add_i32 s17, s17, s10
	s_cmp_lt_i32 s18, 64
	v_readlane_b32 s11, v254, 5
	s_waitcnt vmcnt(0) lgkmcnt(0)
	v_pk_mul_f32 v[2:3], v[2:3], v[6:7]
	v_pk_mul_f32 v[0:1], v[0:1], v[4:5]
	flat_store_dwordx4 v[14:15], v[0:3] offset:64
	s_cbranch_scc1 .LBB0_25

; #define RAW_BARRIER() do { asm volatile("s_waitcnt lgkmcnt(0)" ::: "memory"); __builtin_amdgcn_s_barrier(); } while (0)
; #define GLDS_TILE(kt, st) do { _Pragma("unroll") for (int _i = 0; _i < NP; ++_i) GLDS_PIECE(_i, kt, st); } while (0)
;     ...
;     constexpr int NH = NI >= 4 ? NI / 2 : NI;
;     constexpr int NP = 2 + NB, IVL = (4 * NI) / NP;
;     RAW_BARRIER();
;     GLDS_TILE(0, 0);
;     GLDS_TILE(1, 1);
;     int st = 0;
;     for (int kt = 0; kt < nk - 1; ++kt) {
;         if (NI == 8) asm volatile("s_waitcnt vmcnt(6)" ::: "memory"); else if (NI == 4) asm volatile("s_waitcnt vmcnt(4)" ::: "memory"); else asm volatile("s_waitcnt vmcnt(3)" ::: "memory");
;         RAW_BARRIER();
;         const int s2 = st >= 1 ? st - 1 : 2;
;         const bool ld = kt + 2 < nk;
;         STEP_TILE(st, ld, kt + 2, s2);
;         st = st == 2 ? 0 : st + 1;
;     }
.LBB0_37:
	s_mul_i32 s18, s9, 0x6000
	s_add_i32 s19, s18, 0
	s_waitcnt vmcnt(6)
	v_add_u32_e32 v148, s19, v134
	v_add_u32_e32 v155, s19, v135
	s_waitcnt lgkmcnt(0)
	s_barrier
	ds_read_b128 v[136:139], v148
	ds_read_b128 v[140:143], v148 offset:1024
	ds_read_b128 v[144:147], v148 offset:2048
	ds_read_b128 v[148:151], v148 offset:3072
	ds_read_b128 v[158:161], v155 offset:8192
	ds_read_b128 v[162:165], v155 offset:9216
	ds_read_b128 v[166:169], v155 offset:10240
	ds_read_b128 v[170:173], v155 offset:11264
	s_addk_i32 s18, 0xa000
	s_cmp_gt_i32 s9, 0
	s_setprio 1
	s_waitcnt lgkmcnt(0)
	v_mfma_f32_16x16x32_bf16 v[126:129], v[158:161], v[136:139], v[126:129]
	s_cselect_b32 s18, s18, 0xc000
	v_add_u32_e32 v157, s18, v32
	v_lshl_add_u64 v[152:153], v[132:133], 0, s[10:11]
	v_mfma_f32_16x16x32_bf16 v[110:113], v[158:161], v[140:143], v[110:113]
	s_mov_b64 s[18:19], 0x1f00080
	v_lshl_add_u64 v[208:209], v[130:131], 0, s[10:11]
	v_lshl_add_u64 v[206:207], v[152:153], 0, s[18:19]
	v_mfma_f32_16x16x32_bf16 v[82:85], v[158:161], v[144:147], v[82:85]
	v_add_u32_e32 v205, 0x2000, v157
	v_mfma_f32_16x16x32_bf16 v[50:53], v[158:161], v[148:151], v[50:53]
	v_lshl_add_u64 v[158:159], v[208:209], 0, s[20:21]
	v_mfma_f32_16x16x32_bf16 v[122:125], v[162:165], v[136:139], v[122:125]
	v_readfirstlane_b32 s18, v157
	s_mov_b32 m0, s18
	s_nop 0
	global_load_lds_dwordx4 v[158:159], off
	ds_read_b128 v[158:161], v155 offset:12288
	ds_read_b128 v[174:177], v155 offset:13312
	ds_read_b128 v[178:181], v155 offset:14336
	ds_read_b128 v[182:185], v155 offset:15360
	v_mfma_f32_16x16x32_bf16 v[102:105], v[162:165], v[140:143], v[102:105]
	v_mfma_f32_16x16x32_bf16 v[70:73], v[162:165], v[144:147], v[70:73]
	v_mfma_f32_16x16x32_bf16 v[38:41], v[162:165], v[148:151], v[38:41]
	v_mfma_f32_16x16x32_bf16 v[118:121], v[166:169], v[136:139], v[118:121]
	v_mfma_f32_16x16x32_bf16 v[94:97], v[166:169], v[140:143], v[94:97]
	v_add_u32_e32 v155, 0x1000, v157
	v_lshl_add_u64 v[162:163], v[208:209], 0, s[22:23]
	v_readfirstlane_b32 s18, v155
	s_mov_b32 m0, s18
	s_nop 0
	global_load_lds_dwordx4 v[162:163], off
	v_mfma_f32_16x16x32_bf16 v[62:65], v[166:169], v[144:147], v[62:65]
	v_mfma_f32_16x16x32_bf16 v[28:31], v[166:169], v[148:151], v[28:31]
	v_mfma_f32_16x16x32_bf16 v[114:117], v[170:173], v[136:139], v[114:117]
	v_mfma_f32_16x16x32_bf16 v[86:89], v[170:173], v[140:143], v[86:89]
	v_mfma_f32_16x16x32_bf16 v[54:57], v[170:173], v[144:147], v[54:57]
	v_readfirstlane_b32 s18, v205
	s_mov_b32 m0, s18
	s_nop 0
	global_load_lds_dwordx4 v[206:207], off
	v_mfma_f32_16x16x32_bf16 v[20:23], v[170:173], v[148:151], v[20:23]
	s_waitcnt lgkmcnt(0)
	v_mfma_f32_16x16x32_bf16 v[106:109], v[158:161], v[136:139], v[106:109]
	v_mfma_f32_16x16x32_bf16 v[74:77], v[158:161], v[140:143], v[74:77]
	v_mfma_f32_16x16x32_bf16 v[42:45], v[158:161], v[144:147], v[42:45]
	v_mfma_f32_16x16x32_bf16 v[12:15], v[158:161], v[148:151], v[12:15]
	v_add_u32_e32 v155, 0x3000, v157
	s_mov_b64 s[18:19], 0x1f20080
	v_lshl_add_u64 v[158:159], v[152:153], 0, s[18:19]
	v_readfirstlane_b32 s18, v155
	s_mov_b32 m0, s18
	s_nop 0
	global_load_lds_dwordx4 v[158:159], off
	v_mfma_f32_16x16x32_bf16 v[98:101], v[174:177], v[136:139], v[98:101]
	v_mfma_f32_16x16x32_bf16 v[66:69], v[174:177], v[140:143], v[66:69]
	v_mfma_f32_16x16x32_bf16 v[34:37], v[174:177], v[144:147], v[34:37]
	v_mfma_f32_16x16x32_bf16 v[8:11], v[174:177], v[148:151], v[8:11]
	v_mfma_f32_16x16x32_bf16 v[90:93], v[178:181], v[136:139], v[90:93]
	v_add_u32_e32 v155, 0x4000, v157
	s_mov_b64 s[18:19], 0x1f40080
	v_lshl_add_u64 v[158:159], v[152:153], 0, s[18:19]
	v_readfirstlane_b32 s18, v155
	s_mov_b32 m0, s18
	s_nop 0
	global_load_lds_dwordx4 v[158:159], off
	v_mfma_f32_16x16x32_bf16 v[58:61], v[178:181], v[140:143], v[58:61]
	v_mfma_f32_16x16x32_bf16 v[24:27], v[178:181], v[144:147], v[24:27]
	v_mfma_f32_16x16x32_bf16 v[4:7], v[178:181], v[148:151], v[4:7]
	v_mfma_f32_16x16x32_bf16 v[78:81], v[182:185], v[136:139], v[78:81]
	v_mfma_f32_16x16x32_bf16 v[46:49], v[182:185], v[140:143], v[46:49]
	v_add_u32_e32 v138, 0x5000, v157
	s_mov_b64 s[18:19], 0x1f60080
	v_lshl_add_u64 v[136:137], v[152:153], 0, s[18:19]
	v_readfirstlane_b32 s18, v138
	s_mov_b32 m0, s18
	s_nop 0
	global_load_lds_dwordx4 v[136:137], off
	v_mfma_f32_16x16x32_bf16 v[16:19], v[182:185], v[144:147], v[16:19]
	v_mfma_f32_16x16x32_bf16 v[0:3], v[182:185], v[148:151], v[0:3]
	s_setprio 0
	s_add_i32 s18, s9, 1
	s_cmp_lg_u32 s9, 2
	s_cselect_b32 s9, s18, 0
	s_add_u32 s10, s10, 0x80
	s_addc_u32 s11, s11, 0
	s_cmpk_lg_i32 s10, 0xf00
	s_cbranch_scc1 .LBB0_37
	s_waitcnt vmcnt(6)
	v_add_u32_e32 v32, 0, v134
	v_add_u32_e32 v152, 0, v135
	s_waitcnt lgkmcnt(0)
	s_barrier
; #define RAW_BARRIER() do { asm volatile("s_waitcnt lgkmcnt(0)" ::: "memory"); __builtin_amdgcn_s_barrier(); } while (0)
;     ...
;     asm volatile("s_waitcnt vmcnt(0)" ::: "memory");
;     RAW_BARRIER();
;     STEP_TILE(st, false, 0, 0);
;     RAW_BARRIER();
;     ...
;                 for (int j = 0; j < 4; ++j) { const float a = acc[mi][h * 4 + nn][j]; o[j] = a * __builtin_amdgcn_rcpf(1.f + __expf(-a)) * acc[mi][h * 4 + 2 + nn][j]; }
	ds_read_b128 v[130:133], v32
	ds_read_b128 v[136:139], v32 offset:1024
	ds_read_b128 v[140:143], v32 offset:2048
	ds_read_b128 v[144:147], v32 offset:3072
	ds_read_b128 v[148:151], v152 offset:8192
	ds_read_b128 v[158:161], v152 offset:9216
	ds_read_b128 v[162:165], v152 offset:10240
	ds_read_b128 v[166:169], v152 offset:11264
	s_setprio 1
	s_waitcnt lgkmcnt(0)
	v_mfma_f32_16x16x32_bf16 v[126:129], v[148:151], v[130:133], v[126:129]
	v_mfma_f32_16x16x32_bf16 v[110:113], v[148:151], v[136:139], v[110:113]
	v_mfma_f32_16x16x32_bf16 v[82:85], v[148:151], v[140:143], v[82:85]
	v_mfma_f32_16x16x32_bf16 v[50:53], v[148:151], v[144:147], v[50:53]
	v_mfma_f32_16x16x32_bf16 v[122:125], v[158:161], v[130:133], v[122:125]
	ds_read_b128 v[148:151], v152 offset:12288
	ds_read_b128 v[170:173], v152 offset:13312
	ds_read_b128 v[174:177], v152 offset:14336
	ds_read_b128 v[178:181], v152 offset:15360
	v_mfma_f32_16x16x32_bf16 v[102:105], v[158:161], v[136:139], v[102:105]
	v_mfma_f32_16x16x32_bf16 v[70:73], v[158:161], v[140:143], v[70:73]
	v_mfma_f32_16x16x32_bf16 v[38:41], v[158:161], v[144:147], v[38:41]
	v_mfma_f32_16x16x32_bf16 v[118:121], v[162:165], v[130:133], v[118:121]
	v_mfma_f32_16x16x32_bf16 v[94:97], v[162:165], v[136:139], v[94:97]
	v_mfma_f32_16x16x32_bf16 v[62:65], v[162:165], v[140:143], v[62:65]
	v_mfma_f32_16x16x32_bf16 v[28:31], v[162:165], v[144:147], v[28:31]
	v_mfma_f32_16x16x32_bf16 v[158:161], v[166:169], v[130:133], v[114:117]
	v_mfma_f32_16x16x32_bf16 v[86:89], v[166:169], v[136:139], v[86:89]
	v_mfma_f32_16x16x32_bf16 v[54:57], v[166:169], v[140:143], v[54:57]
	v_mfma_f32_16x16x32_bf16 v[20:23], v[166:169], v[144:147], v[20:23]
	s_waitcnt lgkmcnt(0)
	v_mfma_f32_16x16x32_bf16 v[162:165], v[148:151], v[130:133], v[106:109]
	v_mfma_f32_16x16x32_bf16 v[166:169], v[148:151], v[136:139], v[74:77]
	v_mfma_f32_16x16x32_bf16 v[182:185], v[148:151], v[140:143], v[42:45]
	v_mfma_f32_16x16x32_bf16 v[12:15], v[148:151], v[144:147], v[12:15]
	v_mfma_f32_16x16x32_bf16 v[148:151], v[170:173], v[130:133], v[98:101]
	v_mfma_f32_16x16x32_bf16 v[206:209], v[170:173], v[136:139], v[66:69]
	v_mfma_f32_16x16x32_bf16 v[210:213], v[170:173], v[140:143], v[34:37]
	v_mfma_f32_16x16x32_bf16 v[170:173], v[170:173], v[144:147], v[8:11]
	v_mfma_f32_16x16x32_bf16 v[214:217], v[174:177], v[130:133], v[90:93]
	v_mfma_f32_16x16x32_bf16 v[218:221], v[174:177], v[136:139], v[58:61]
	v_mfma_f32_16x16x32_bf16 v[222:225], v[174:177], v[140:143], v[24:27]
	v_mfma_f32_16x16x32_bf16 v[4:7], v[174:177], v[144:147], v[4:7]
	v_mfma_f32_16x16x32_bf16 v[130:133], v[178:181], v[130:133], v[78:81]
	v_mfma_f32_16x16x32_bf16 v[134:137], v[178:181], v[136:139], v[46:49]
	v_mfma_f32_16x16x32_bf16 v[138:141], v[178:181], v[140:143], v[16:19]
	v_mfma_f32_16x16x32_bf16 v[142:145], v[178:181], v[144:147], v[0:3]
	s_setprio 0
	s_waitcnt vmcnt(0)
	s_waitcnt lgkmcnt(0)
	s_barrier
	ds_read_b128 v[174:177], v32 offset:24576
	ds_read_b128 v[178:181], v32 offset:25600
	ds_read_b128 v[226:229], v32 offset:26624
	ds_read_b128 v[230:233], v32 offset:27648
	ds_read_b128 v[0:3], v152 offset:32768
	ds_read_b128 v[8:11], v152 offset:33792
	ds_read_b128 v[16:19], v152 offset:34816
	ds_read_b128 v[24:27], v152 offset:35840
	s_setprio 1
	s_waitcnt lgkmcnt(0)
	v_mfma_f32_16x16x32_bf16 v[126:129], v[0:3], v[174:177], v[126:129]
	v_mfma_f32_16x16x32_bf16 v[106:109], v[0:3], v[178:181], v[110:113]
	v_mfma_f32_16x16x32_bf16 v[90:93], v[0:3], v[226:229], v[82:85]
	v_mfma_f32_16x16x32_bf16 v[74:77], v[0:3], v[230:233], v[50:53]
	v_mfma_f32_16x16x32_bf16 v[114:117], v[8:11], v[174:177], v[122:125]
	ds_read_b128 v[0:3], v152 offset:36864
	ds_read_b128 v[46:49], v152 offset:37888
	s_nop 0
	ds_read_b128 v[122:125], v152 offset:38912
	ds_read_b128 v[234:237], v152 offset:39936
	v_mfma_f32_16x16x32_bf16 v[98:101], v[8:11], v[178:181], v[102:105]
	v_mfma_f32_16x16x32_bf16 v[82:85], v[8:11], v[226:229], v[70:73]
	v_mfma_f32_16x16x32_bf16 v[66:69], v[8:11], v[230:233], v[38:41]
	v_mfma_f32_16x16x32_bf16 v[238:241], v[16:19], v[174:177], v[118:121]
	v_mfma_f32_16x16x32_bf16 v[110:113], v[16:19], v[178:181], v[94:97]
	v_mfma_f32_16x16x32_bf16 v[94:97], v[16:19], v[226:229], v[62:65]
	v_mfma_f32_16x16x32_bf16 v[78:81], v[16:19], v[230:233], v[28:31]
	v_mfma_f32_16x16x32_bf16 v[158:161], v[24:27], v[174:177], v[158:161]
	v_mfma_f32_16x16x32_bf16 v[102:105], v[24:27], v[178:181], v[86:89]
	v_mfma_f32_16x16x32_bf16 v[86:89], v[24:27], v[226:229], v[54:57]
	v_mfma_f32_16x16x32_bf16 v[70:73], v[24:27], v[230:233], v[20:23]
	s_waitcnt lgkmcnt(0)
	v_mfma_f32_16x16x32_bf16 v[58:61], v[0:3], v[174:177], v[162:165]
	v_mfma_f32_16x16x32_bf16 v[42:45], v[0:3], v[178:181], v[166:169]
	v_mfma_f32_16x16x32_bf16 v[24:27], v[0:3], v[226:229], v[182:185]
	v_mfma_f32_16x16x32_bf16 v[8:11], v[0:3], v[230:233], v[12:15]
	v_mfma_f32_16x16x32_bf16 v[50:53], v[46:49], v[174:177], v[148:151]
	v_mfma_f32_16x16x32_bf16 v[34:37], v[46:49], v[178:181], v[206:209]
	v_mfma_f32_16x16x32_bf16 v[16:19], v[46:49], v[226:229], v[210:213]
	v_mfma_f32_16x16x32_bf16 v[0:3], v[46:49], v[230:233], v[170:173]
	v_mfma_f32_16x16x32_bf16 v[62:65], v[122:125], v[174:177], v[214:217]
	v_mfma_f32_16x16x32_bf16 v[46:49], v[122:125], v[178:181], v[218:221]
	v_mfma_f32_16x16x32_bf16 v[28:31], v[122:125], v[226:229], v[222:225]
	v_mfma_f32_16x16x32_bf16 v[12:15], v[122:125], v[230:233], v[4:7]
	v_mfma_f32_16x16x32_bf16 v[54:57], v[234:237], v[174:177], v[130:133]
	v_mfma_f32_16x16x32_bf16 v[38:41], v[234:237], v[178:181], v[134:137]
	v_mfma_f32_16x16x32_bf16 v[20:23], v[234:237], v[226:229], v[138:141]
	v_mfma_f32_16x16x32_bf16 v[4:7], v[234:237], v[230:233], v[142:145]
	s_setprio 0
	v_mul_f32_e32 v120, 0xbfb8aa3b, v126
	v_mul_f32_e32 v121, 0xbfb8aa3b, v127
	v_mul_f32_e32 v122, 0xbfb8aa3b, v128
	v_mul_f32_e32 v123, 0xbfb8aa3b, v129
	v_exp_f32_e32 v120, v120
	v_exp_f32_e32 v121, v121
	v_exp_f32_e32 v122, v122
	v_exp_f32_e32 v123, v123
	v_add_f32_e32 v120, 1.0, v120
	v_add_f32_e32 v121, 1.0, v121
	v_add_f32_e32 v122, 1.0, v122
	v_add_f32_e32 v123, 1.0, v123
	v_rcp_f32_e32 v120, v120
	v_rcp_f32_e32 v121, v121
	v_rcp_f32_e32 v122, v122
	v_rcp_f32_e32 v123, v123
	v_mov_b32_e32 v32, v186
	v_pk_mul_f32 v[120:121], v[126:127], v[120:121]
	s_waitcnt lgkmcnt(0)
	v_pk_mul_f32 v[122:123], v[128:129], v[122:123]
	s_barrier
; DEV unsigned pk_bf16(float lo, float hi) { const f32x2_t f = {lo, hi}; const bf16x2_t b = __builtin_convertvector(f, bf16x2_t); return __builtin_bit_cast(unsigned, b); }
; DEV void wst_put4(char* wsm, int row, int col, float a, float b, float c, float d) { uint2 w; w.x = pk_bf16(a, b); w.y = pk_bf16(c, d); *(uint2*)(wsm + row * WST_ROW + col * 2) = w; }
;     ...
;     for (int h = 0; h < 2; ++h) {
;         const int ch0 = (nt * 4 + wn * 2 + h) * 32 + fq * 4;
; #pragma unroll
;         for (int mi = 0; mi < 4; ++mi)
; #pragma unroll
;             for (int nn = 0; nn < 2; ++nn) {
;                 float o[4];
; #pragma unroll
;                 for (int j = 0; j < 4; ++j) { const float a = acc[mi][h * 4 + nn][j]; o[j] = a * __builtin_amdgcn_rcpf(1.f + __expf(-a)) * acc[mi][h * 4 + 2 + nn][j]; }
;                 wst_put4(wsm, mi * 16 + fr, h * 32 + nn * 16 + fq * 4, o[0], o[1], o[2], o[3]);
;             }
	s_movk_i32 s9, 0x4400
	v_lshrrev_b32_e32 v118, 6, v32
	v_pk_mul_f32 v[120:121], v[120:121], v[238:239]
	v_pk_mul_f32 v[122:123], v[122:123], v[240:241]
	v_and_b32_e32 v119, 15, v32
	v_mul_lo_u32 v118, v118, s9
	v_cvt_pk_bf16_f32 v120, v120, v121
	v_cvt_pk_bf16_f32 v121, v122, v123
	v_lshrrev_b32_e32 v122, 1, v32
	v_add_u32_e32 v118, 0, v118
	v_mul_u32_u24_e32 v119, 0x110, v119
	v_and_b32_e32 v122, 24, v122
	v_add3_u32 v119, v118, v119, v122
	v_mul_f32_e32 v122, 0xbfb8aa3b, v114
	v_mul_f32_e32 v123, 0xbfb8aa3b, v115
	v_exp_f32_e32 v122, v122
	v_exp_f32_e32 v123, v123
	s_movk_i32 s9, 0x1600
	s_lshl_b32 s8, s8, 7
	v_add_f32_e32 v122, 1.0, v122
	v_add_f32_e32 v123, 1.0, v123
	v_rcp_f32_e32 v122, v122
	v_rcp_f32_e32 v123, v123
	s_nop 0
	v_pk_mul_f32 v[114:115], v[114:115], v[122:123]
	v_mul_f32_e32 v122, 0xbfb8aa3b, v116
	v_mul_f32_e32 v123, 0xbfb8aa3b, v117
	v_exp_f32_e32 v122, v122
	v_exp_f32_e32 v123, v123
	v_pk_mul_f32 v[114:115], v[114:115], v[158:159]
	v_add_f32_e32 v122, 1.0, v122
	v_add_f32_e32 v123, 1.0, v123
	v_rcp_f32_e32 v122, v122
	v_rcp_f32_e32 v123, v123
	v_cvt_pk_bf16_f32 v114, v114, v115
	v_pk_mul_f32 v[116:117], v[116:117], v[122:123]
	s_nop 0
	v_pk_mul_f32 v[116:117], v[116:117], v[160:161]
	s_nop 0
	v_cvt_pk_bf16_f32 v115, v116, v117
	s_waitcnt vmcnt(0)
	ds_write2_b64 v119, v[120:121], v[114:115] offset1:4
	v_mul_f32_e32 v114, 0xbfb8aa3b, v106
	v_mul_f32_e32 v115, 0xbfb8aa3b, v107
	v_exp_f32_e32 v114, v114
	v_exp_f32_e32 v115, v115
	v_add_f32_e32 v114, 1.0, v114
	v_add_f32_e32 v115, 1.0, v115
	v_rcp_f32_e32 v114, v114
	v_rcp_f32_e32 v115, v115
	s_nop 0
	v_pk_mul_f32 v[106:107], v[106:107], v[114:115]
	s_nop 0
	v_pk_mul_f32 v[106:107], v[106:107], v[110:111]
	v_mul_f32_e32 v110, 0xbfb8aa3b, v108
	v_mul_f32_e32 v111, 0xbfb8aa3b, v109
	v_exp_f32_e32 v110, v110
	v_exp_f32_e32 v111, v111
	v_cvt_pk_bf16_f32 v106, v106, v107
	v_add_f32_e32 v110, 1.0, v110
	v_add_f32_e32 v111, 1.0, v111
	v_rcp_f32_e32 v110, v110
	v_rcp_f32_e32 v111, v111
	s_nop 0
	v_pk_mul_f32 v[108:109], v[108:109], v[110:111]
	s_nop 0
	v_pk_mul_f32 v[108:109], v[108:109], v[112:113]
	s_nop 0
	v_cvt_pk_bf16_f32 v107, v108, v109
	v_mul_f32_e32 v108, 0xbfb8aa3b, v98
	v_mul_f32_e32 v109, 0xbfb8aa3b, v99
	v_exp_f32_e32 v108, v108
	v_exp_f32_e32 v109, v109
	v_add_f32_e32 v108, 1.0, v108
	v_add_f32_e32 v109, 1.0, v109
	v_rcp_f32_e32 v108, v108
	v_rcp_f32_e32 v109, v109
	s_nop 0
	v_pk_mul_f32 v[98:99], v[98:99], v[108:109]
	s_nop 0
	v_pk_mul_f32 v[98:99], v[98:99], v[102:103]
	v_mul_f32_e32 v102, 0xbfb8aa3b, v100
	v_mul_f32_e32 v103, 0xbfb8aa3b, v101
	v_exp_f32_e32 v102, v102
	v_exp_f32_e32 v103, v103
	v_add_f32_e32 v102, 1.0, v102
	v_add_f32_e32 v103, 1.0, v103
	v_rcp_f32_e32 v102, v102
	v_rcp_f32_e32 v103, v103
	s_nop 0
	v_pk_mul_f32 v[100:101], v[100:101], v[102:103]
	v_cvt_pk_bf16_f32 v102, v98, v99
	v_mul_f32_e32 v99, 0xbfb8aa3b, v90
	v_exp_f32_e32 v99, v99
	v_pk_mul_f32 v[100:101], v[100:101], v[104:105]
	v_add_u32_e32 v98, 0x1000, v119
	v_cvt_pk_bf16_f32 v103, v100, v101
	v_add_f32_e32 v99, 1.0, v99
	v_rcp_f32_e32 v100, v99
	v_mul_f32_e32 v99, 0xbfb8aa3b, v91
	v_exp_f32_e32 v99, v99
	ds_write2_b64 v98, v[106:107], v[102:103] offset0:32 offset1:36
	v_add_f32_e32 v99, 1.0, v99
	v_rcp_f32_e32 v101, v99
	s_nop 0
	v_pk_mul_f32 v[90:91], v[90:91], v[100:101]
	s_nop 0
	v_pk_mul_f32 v[90:91], v[90:91], v[94:95]
	v_mul_f32_e32 v94, 0xbfb8aa3b, v92
	v_mul_f32_e32 v95, 0xbfb8aa3b, v93
	v_exp_f32_e32 v94, v94
	v_exp_f32_e32 v95, v95
	v_cvt_pk_bf16_f32 v90, v90, v91
	v_add_f32_e32 v94, 1.0, v94
	v_add_f32_e32 v95, 1.0, v95
	v_rcp_f32_e32 v94, v94
	v_rcp_f32_e32 v95, v95
	s_nop 0
	v_pk_mul_f32 v[92:93], v[92:93], v[94:95]
	s_nop 0
	v_pk_mul_f32 v[92:93], v[92:93], v[96:97]
	s_nop 0
	v_cvt_pk_bf16_f32 v91, v92, v93
	v_mul_f32_e32 v92, 0xbfb8aa3b, v82
	v_mul_f32_e32 v93, 0xbfb8aa3b, v83
	v_exp_f32_e32 v92, v92
	v_exp_f32_e32 v93, v93
	v_add_f32_e32 v92, 1.0, v92
	v_add_f32_e32 v93, 1.0, v93
	v_rcp_f32_e32 v92, v92
	v_rcp_f32_e32 v93, v93
	s_nop 0
	v_pk_mul_f32 v[82:83], v[82:83], v[92:93]
	s_nop 0
	v_pk_mul_f32 v[82:83], v[82:83], v[86:87]
	v_mul_f32_e32 v86, 0xbfb8aa3b, v84
	v_mul_f32_e32 v87, 0xbfb8aa3b, v85
	v_exp_f32_e32 v86, v86
	v_exp_f32_e32 v87, v87
	v_add_f32_e32 v86, 1.0, v86
	v_add_f32_e32 v87, 1.0, v87
	v_rcp_f32_e32 v86, v86
	v_rcp_f32_e32 v87, v87
	s_nop 0
	v_pk_mul_f32 v[84:85], v[84:85], v[86:87]
	v_cvt_pk_bf16_f32 v86, v82, v83
	v_mul_f32_e32 v83, 0xbfb8aa3b, v74
	v_exp_f32_e32 v83, v83
	v_pk_mul_f32 v[84:85], v[84:85], v[88:89]
	v_add_u32_e32 v82, 0x2000, v119
	v_cvt_pk_bf16_f32 v87, v84, v85
	v_add_f32_e32 v83, 1.0, v83
	v_rcp_f32_e32 v84, v83
	v_mul_f32_e32 v83, 0xbfb8aa3b, v75
	v_exp_f32_e32 v83, v83
	ds_write2_b64 v82, v[90:91], v[86:87] offset0:64 offset1:68
	v_add_f32_e32 v83, 1.0, v83
	v_rcp_f32_e32 v85, v83
	s_nop 0
	v_pk_mul_f32 v[74:75], v[74:75], v[84:85]
	s_nop 0
	v_pk_mul_f32 v[74:75], v[74:75], v[78:79]
	v_mul_f32_e32 v78, 0xbfb8aa3b, v76
	v_mul_f32_e32 v79, 0xbfb8aa3b, v77
	v_exp_f32_e32 v78, v78
	v_exp_f32_e32 v79, v79
	v_cvt_pk_bf16_f32 v74, v74, v75
	v_add_f32_e32 v78, 1.0, v78
	v_add_f32_e32 v79, 1.0, v79
	v_rcp_f32_e32 v78, v78
	v_rcp_f32_e32 v79, v79
	s_nop 0
	v_pk_mul_f32 v[76:77], v[76:77], v[78:79]
	s_nop 0
	v_pk_mul_f32 v[76:77], v[76:77], v[80:81]
	s_nop 0
	v_cvt_pk_bf16_f32 v75, v76, v77
	v_mul_f32_e32 v76, 0xbfb8aa3b, v66
	v_mul_f32_e32 v77, 0xbfb8aa3b, v67
	v_exp_f32_e32 v76, v76
	v_exp_f32_e32 v77, v77
	v_add_f32_e32 v76, 1.0, v76
	v_add_f32_e32 v77, 1.0, v77
	v_rcp_f32_e32 v76, v76
	v_rcp_f32_e32 v77, v77
	s_nop 0
	v_pk_mul_f32 v[66:67], v[66:67], v[76:77]
	s_nop 0
	v_pk_mul_f32 v[66:67], v[66:67], v[70:71]
	v_mul_f32_e32 v70, 0xbfb8aa3b, v68
;     __device__ __forceinline__ bf16_t* Act() const { return (bf16_t*)(ws + OFF_Act); }
; DEV void wst_put4(char* wsm, int row, int col, float a, float b, float c, float d) { uint2 w; w.x = pk_bf16(a, b); w.y = pk_bf16(c, d); *(uint2*)(wsm + row * WST_ROW + col * 2) = w; }
; template <int NCOLS>
; DEV void wst_flush(const char* wsm, bf16_t* dst, int ld, int lane) {
;     constexpr int CPR = NCOLS / 8, RPI = 64 / CPR;
;     asm volatile("s_waitcnt lgkmcnt(0)" ::: "memory");
;     const int r0 = lane / CPR, ch = lane % CPR;
; #pragma unroll
;     for (int it = 0; it < 64 / RPI; ++it) {
;         const int row = it * RPI + r0;
;         const uint4 v = *(const uint4*)(wsm + row * WST_ROW + ch * 16);
;         *(uint4*)(dst + (size_t)row * ld + ch * 8) = v;
;     ...
;     for (int h = 0; h < 2; ++h) {
;         const int ch0 = (nt * 4 + wn * 2 + h) * 32 + fq * 4;
; #pragma unroll
;         for (int mi = 0; mi < 4; ++mi)
; #pragma unroll
;             for (int nn = 0; nn < 2; ++nn) {
;                 float o[4];
; #pragma unroll
;                 for (int j = 0; j < 4; ++j) { const float a = acc[mi][h * 4 + nn][j]; o[j] = a * __builtin_amdgcn_rcpf(1.f + __expf(-a)) * acc[mi][h * 4 + 2 + nn][j]; }
;                 wst_put4(wsm, mi * 16 + fr, h * 32 + nn * 16 + fq * 4, o[0], o[1], o[2], o[3]);
;             }
;         (void)ch0;
;     }
;     wst_flush<64>(wsm, p.Act() + (size_t)(mt * 128 + wm * 64) * DFF + (nt * 4 + wn * 2) * 32, DFF, lane);
	v_mul_f32_e32 v71, 0xbfb8aa3b, v69
	v_exp_f32_e32 v70, v70
	v_exp_f32_e32 v71, v71
	v_add_f32_e32 v70, 1.0, v70
	v_add_f32_e32 v71, 1.0, v71
	v_rcp_f32_e32 v70, v70
	v_rcp_f32_e32 v71, v71
	s_nop 0
	v_pk_mul_f32 v[68:69], v[68:69], v[70:71]
	v_cvt_pk_bf16_f32 v70, v66, v67
	v_mul_f32_e32 v67, 0xbfb8aa3b, v58
	v_exp_f32_e32 v67, v67
	v_pk_mul_f32 v[68:69], v[68:69], v[72:73]
	v_add_u32_e32 v66, 0x3000, v119
	v_cvt_pk_bf16_f32 v71, v68, v69
	v_add_f32_e32 v67, 1.0, v67
	v_rcp_f32_e32 v68, v67
	v_mul_f32_e32 v67, 0xbfb8aa3b, v59
	v_exp_f32_e32 v67, v67
	ds_write2_b64 v66, v[74:75], v[70:71] offset0:96 offset1:100
	v_add_f32_e32 v67, 1.0, v67
	v_rcp_f32_e32 v69, v67
	s_nop 0
	v_pk_mul_f32 v[58:59], v[58:59], v[68:69]
	s_nop 0
	v_pk_mul_f32 v[58:59], v[58:59], v[62:63]
	v_mul_f32_e32 v62, 0xbfb8aa3b, v60
	v_mul_f32_e32 v63, 0xbfb8aa3b, v61
	v_exp_f32_e32 v62, v62
	v_exp_f32_e32 v63, v63
	v_cvt_pk_bf16_f32 v58, v58, v59
	v_add_f32_e32 v62, 1.0, v62
	v_add_f32_e32 v63, 1.0, v63
	v_rcp_f32_e32 v62, v62
	v_rcp_f32_e32 v63, v63
	s_nop 0
	v_pk_mul_f32 v[60:61], v[60:61], v[62:63]
	s_nop 0
	v_pk_mul_f32 v[60:61], v[60:61], v[64:65]
	s_nop 0
	v_cvt_pk_bf16_f32 v59, v60, v61
	v_mul_f32_e32 v60, 0xbfb8aa3b, v50
	v_mul_f32_e32 v61, 0xbfb8aa3b, v51
	v_exp_f32_e32 v60, v60
	v_exp_f32_e32 v61, v61
	v_add_f32_e32 v60, 1.0, v60
	v_add_f32_e32 v61, 1.0, v61
	v_rcp_f32_e32 v60, v60
	v_rcp_f32_e32 v61, v61
	s_nop 0
	v_pk_mul_f32 v[50:51], v[50:51], v[60:61]
	s_nop 0
	v_pk_mul_f32 v[50:51], v[50:51], v[54:55]
	v_mul_f32_e32 v54, 0xbfb8aa3b, v52
	v_mul_f32_e32 v55, 0xbfb8aa3b, v53
	v_exp_f32_e32 v54, v54
	v_exp_f32_e32 v55, v55
	v_cvt_pk_bf16_f32 v50, v50, v51
	v_add_f32_e32 v54, 1.0, v54
	v_add_f32_e32 v55, 1.0, v55
	v_rcp_f32_e32 v54, v54
	v_rcp_f32_e32 v55, v55
	s_nop 0
	v_pk_mul_f32 v[52:53], v[52:53], v[54:55]
	s_nop 0
	v_pk_mul_f32 v[52:53], v[52:53], v[56:57]
	s_nop 0
	v_cvt_pk_bf16_f32 v51, v52, v53
	ds_write2_b64 v119, v[58:59], v[50:51] offset0:8 offset1:12
	v_mul_f32_e32 v50, 0xbfb8aa3b, v42
	v_mul_f32_e32 v51, 0xbfb8aa3b, v43
	v_exp_f32_e32 v50, v50
	v_exp_f32_e32 v51, v51
	v_add_f32_e32 v50, 1.0, v50
	v_add_f32_e32 v51, 1.0, v51
	v_rcp_f32_e32 v50, v50
	v_rcp_f32_e32 v51, v51
	s_nop 0
	v_pk_mul_f32 v[42:43], v[42:43], v[50:51]
	s_nop 0
	v_pk_mul_f32 v[42:43], v[42:43], v[46:47]
	v_mul_f32_e32 v46, 0xbfb8aa3b, v44
	v_mul_f32_e32 v47, 0xbfb8aa3b, v45
	v_exp_f32_e32 v46, v46
	v_exp_f32_e32 v47, v47
	v_cvt_pk_bf16_f32 v42, v42, v43
	v_add_f32_e32 v46, 1.0, v46
	v_add_f32_e32 v47, 1.0, v47
	v_rcp_f32_e32 v46, v46
	v_rcp_f32_e32 v47, v47
	s_nop 0
	v_pk_mul_f32 v[44:45], v[44:45], v[46:47]
	s_nop 0
	v_pk_mul_f32 v[44:45], v[44:45], v[48:49]
	s_nop 0
	v_cvt_pk_bf16_f32 v43, v44, v45
	v_mul_f32_e32 v44, 0xbfb8aa3b, v34
	v_mul_f32_e32 v45, 0xbfb8aa3b, v35
	v_exp_f32_e32 v44, v44
	v_exp_f32_e32 v45, v45
	v_add_f32_e32 v44, 1.0, v44
	v_add_f32_e32 v45, 1.0, v45
	v_rcp_f32_e32 v44, v44
	v_rcp_f32_e32 v45, v45
	s_nop 0
	v_pk_mul_f32 v[34:35], v[34:35], v[44:45]
	s_nop 0
	v_pk_mul_f32 v[34:35], v[34:35], v[38:39]
	v_mul_f32_e32 v38, 0xbfb8aa3b, v36
	v_mul_f32_e32 v39, 0xbfb8aa3b, v37
	v_exp_f32_e32 v38, v38
	v_exp_f32_e32 v39, v39
	v_cvt_pk_bf16_f32 v34, v34, v35
	v_add_f32_e32 v38, 1.0, v38
	v_add_f32_e32 v39, 1.0, v39
	v_rcp_f32_e32 v38, v38
	v_rcp_f32_e32 v39, v39
	s_nop 0
	v_pk_mul_f32 v[36:37], v[36:37], v[38:39]
	s_nop 0
	v_pk_mul_f32 v[36:37], v[36:37], v[40:41]
	s_nop 0
	v_cvt_pk_bf16_f32 v35, v36, v37
	ds_write2_b64 v98, v[42:43], v[34:35] offset0:40 offset1:44
	v_mul_f32_e32 v34, 0xbfb8aa3b, v24
	v_mul_f32_e32 v35, 0xbfb8aa3b, v25
	v_exp_f32_e32 v34, v34
	v_exp_f32_e32 v35, v35
	v_add_f32_e32 v34, 1.0, v34
	v_add_f32_e32 v35, 1.0, v35
	v_rcp_f32_e32 v34, v34
	v_rcp_f32_e32 v35, v35
	s_nop 0
	v_pk_mul_f32 v[24:25], v[24:25], v[34:35]
	s_nop 0
	v_pk_mul_f32 v[24:25], v[24:25], v[28:29]
	v_mul_f32_e32 v28, 0xbfb8aa3b, v26
	v_mul_f32_e32 v29, 0xbfb8aa3b, v27
	v_exp_f32_e32 v28, v28
	v_exp_f32_e32 v29, v29
	v_cvt_pk_bf16_f32 v24, v24, v25
	v_add_f32_e32 v28, 1.0, v28
	v_add_f32_e32 v29, 1.0, v29
	v_rcp_f32_e32 v28, v28
	v_rcp_f32_e32 v29, v29
	s_nop 0
	v_pk_mul_f32 v[26:27], v[26:27], v[28:29]
	s_nop 0
	v_pk_mul_f32 v[26:27], v[26:27], v[30:31]
	s_nop 0
	v_cvt_pk_bf16_f32 v25, v26, v27
	v_mul_f32_e32 v26, 0xbfb8aa3b, v16
	v_mul_f32_e32 v27, 0xbfb8aa3b, v17
	v_exp_f32_e32 v26, v26
	v_exp_f32_e32 v27, v27
	v_add_f32_e32 v26, 1.0, v26
	v_add_f32_e32 v27, 1.0, v27
	v_rcp_f32_e32 v26, v26
	v_rcp_f32_e32 v27, v27
	s_nop 0
	v_pk_mul_f32 v[16:17], v[16:17], v[26:27]
	s_nop 0
	v_pk_mul_f32 v[16:17], v[16:17], v[20:21]
	v_mul_f32_e32 v20, 0xbfb8aa3b, v18
	v_mul_f32_e32 v21, 0xbfb8aa3b, v19
	v_exp_f32_e32 v20, v20
	v_exp_f32_e32 v21, v21
	v_cvt_pk_bf16_f32 v16, v16, v17
	v_add_f32_e32 v20, 1.0, v20
	v_add_f32_e32 v21, 1.0, v21
	v_rcp_f32_e32 v20, v20
	v_rcp_f32_e32 v21, v21
	s_nop 0
	v_pk_mul_f32 v[18:19], v[18:19], v[20:21]
	s_nop 0
	v_pk_mul_f32 v[18:19], v[18:19], v[22:23]
	s_nop 0
	v_cvt_pk_bf16_f32 v17, v18, v19
	ds_write2_b64 v82, v[24:25], v[16:17] offset0:72 offset1:76
	v_mul_f32_e32 v16, 0xbfb8aa3b, v8
	v_mul_f32_e32 v17, 0xbfb8aa3b, v9
	v_exp_f32_e32 v16, v16
	v_exp_f32_e32 v17, v17
	v_add_f32_e32 v16, 1.0, v16
	v_add_f32_e32 v17, 1.0, v17
	v_rcp_f32_e32 v16, v16
	v_rcp_f32_e32 v17, v17
	s_nop 0
	v_pk_mul_f32 v[8:9], v[8:9], v[16:17]
	s_nop 0
	v_pk_mul_f32 v[8:9], v[8:9], v[12:13]
	v_mul_f32_e32 v12, 0xbfb8aa3b, v10
	v_mul_f32_e32 v13, 0xbfb8aa3b, v11
	v_exp_f32_e32 v12, v12
	v_exp_f32_e32 v13, v13
	v_cvt_pk_bf16_f32 v8, v8, v9
	v_add_f32_e32 v12, 1.0, v12
	v_add_f32_e32 v13, 1.0, v13
	v_rcp_f32_e32 v12, v12
	v_rcp_f32_e32 v13, v13
	s_nop 0
	v_pk_mul_f32 v[10:11], v[10:11], v[12:13]
	s_nop 0
	v_pk_mul_f32 v[10:11], v[10:11], v[14:15]
	s_nop 0
	v_cvt_pk_bf16_f32 v9, v10, v11
	v_mul_f32_e32 v10, 0xbfb8aa3b, v0
	v_mul_f32_e32 v11, 0xbfb8aa3b, v1
	v_exp_f32_e32 v10, v10
	v_exp_f32_e32 v11, v11
	v_add_f32_e32 v10, 1.0, v10
	v_add_f32_e32 v11, 1.0, v11
	v_rcp_f32_e32 v10, v10
	v_rcp_f32_e32 v11, v11
	s_nop 0
	v_pk_mul_f32 v[0:1], v[0:1], v[10:11]
	s_nop 0
	v_pk_mul_f32 v[0:1], v[0:1], v[4:5]
	v_mul_f32_e32 v4, 0xbfb8aa3b, v2
	v_mul_f32_e32 v5, 0xbfb8aa3b, v3
	v_exp_f32_e32 v4, v4
	v_exp_f32_e32 v5, v5
	v_cvt_pk_bf16_f32 v0, v0, v1
	v_add_f32_e32 v4, 1.0, v4
	v_add_f32_e32 v5, 1.0, v5
	v_rcp_f32_e32 v4, v4
	v_rcp_f32_e32 v5, v5
	s_nop 0
	v_pk_mul_f32 v[2:3], v[2:3], v[4:5]
	s_nop 0
	v_pk_mul_f32 v[2:3], v[2:3], v[6:7]
	v_bfe_u32 v6, v32, 3, 3
	v_cvt_pk_bf16_f32 v1, v2, v3
	ds_write2_b64 v66, v[8:9], v[0:1] offset0:104 offset1:108
	v_ashrrev_i32_e32 v0, 1, v32
	v_and_b32_e32 v0, 0xffffffc0, v0
	v_lshl_add_u32 v2, s17, 7, v0
	v_mov_b64_e32 v[0:1], s[6:7]
	v_mad_i64_i32 v[0:1], s[10:11], v2, s9, v[0:1]
	v_and_or_b32 v2, v32, 64, s8
	v_ashrrev_i32_e32 v3, 31, v2
	v_lshl_add_u64 v[0:1], v[2:3], 2, v[0:1]
	v_lshlrev_b32_e32 v2, 4, v32
	v_and_b32_e32 v32, 0x70, v2
	v_lshl_add_u64 v[4:5], v[0:1], 0, v[32:33]
	v_and_b32_e32 v2, 64, v2
	v_mov_b32_e32 v3, 0
	v_lshl_add_u64 v[4:5], v[4:5], 0, v[2:3]
	v_mul_u32_u24_e32 v0, 0x110, v6
	s_waitcnt lgkmcnt(0)
; template <int NCOLS>
; DEV void wst_flush(const char* wsm, bf16_t* dst, int ld, int lane) {
;     constexpr int CPR = NCOLS / 8, RPI = 64 / CPR;
;     asm volatile("s_waitcnt lgkmcnt(0)" ::: "memory");
;     const int r0 = lane / CPR, ch = lane % CPR;
; #pragma unroll
;     for (int it = 0; it < 64 / RPI; ++it) {
;         const int row = it * RPI + r0;
;         const uint4 v = *(const uint4*)(wsm + row * WST_ROW + ch * 16);
;         *(uint4*)(dst + (size_t)row * ld + ch * 8) = v;
;     }
	v_add3_u32 v10, v118, v32, v0
	ds_read_b128 v[0:3], v10
	v_lshrrev_b32_e32 v32, 1, v6
	v_mul_u32_u24_e32 v32, 0x2c00, v32
	v_and_b32_e32 v6, 1, v6
	v_lshl_or_b32 v32, v6, 6, v32
	v_lshl_add_u64 v[6:7], v[4:5], 0, v[32:33]
	s_mov_b32 s8, 0xb000
	s_waitcnt lgkmcnt(0)
	flat_store_dwordx4 v[6:7], v[0:3]
	ds_read_b128 v[0:3], v10 offset:2176
	v_add_co_u32_e32 v8, vcc, s8, v6
	s_mov_b32 s8, 0x16000
	s_nop 0
	v_addc_co_u32_e32 v9, vcc, 0, v7, vcc
	s_waitcnt lgkmcnt(0)
	flat_store_dwordx4 v[8:9], v[0:3]
	ds_read_b128 v[0:3], v10 offset:4352
	v_add_co_u32_e32 v8, vcc, s8, v6
	s_mov_b32 s8, 0x21000
	s_nop 0
	v_addc_co_u32_e32 v9, vcc, 0, v7, vcc
	s_waitcnt lgkmcnt(0)
	flat_store_dwordx4 v[8:9], v[0:3]
	ds_read_b128 v[0:3], v10 offset:6528
	v_add_co_u32_e32 v8, vcc, s8, v6
	s_mov_b32 s8, 0x2c000
	s_nop 0
	v_addc_co_u32_e32 v9, vcc, 0, v7, vcc
	s_waitcnt lgkmcnt(0)
	flat_store_dwordx4 v[8:9], v[0:3]
	ds_read_b128 v[0:3], v10 offset:8704
	v_add_co_u32_e32 v6, vcc, s8, v6
	v_readlane_b32 s8, v254, 4
	s_nop 0
	v_addc_co_u32_e32 v7, vcc, 0, v7, vcc
	s_waitcnt lgkmcnt(0)
	flat_store_dwordx4 v[6:7], v[0:3]
	ds_read_b128 v[0:3], v10 offset:10880
	v_add_u32_e32 v6, 0x37000, v32
	v_mov_b32_e32 v7, v33
	v_lshl_add_u64 v[6:7], v[4:5], 0, v[6:7]
	s_add_i32 s16, s16, s8
	s_waitcnt lgkmcnt(0)
	flat_store_dwordx4 v[6:7], v[0:3]
	ds_read_b128 v[0:3], v10 offset:13056
	v_add_u32_e32 v6, 0x42000, v32
	v_mov_b32_e32 v7, v33
	v_lshl_add_u64 v[6:7], v[4:5], 0, v[6:7]
	v_add_u32_e32 v32, 0x4d000, v32
	s_waitcnt lgkmcnt(0)
	flat_store_dwordx4 v[6:7], v[0:3]
	ds_read_b128 v[0:3], v10 offset:15232
	v_lshl_add_u64 v[4:5], v[4:5], 0, v[32:33]
	s_cmpk_gt_i32 s16, 0xb15
	v_readlane_b32 s9, v254, 5
	s_waitcnt lgkmcnt(0)
	flat_store_dwordx4 v[4:5], v[0:3]
	s_cbranch_scc0 .LBB0_32

; DEV int tid_opaque() { int t = threadIdx.x; asm volatile("" : "+v"(t)); return t; }
; template <bool SB> ...
;     const int t = tid_opaque(), lane = t & 63, wid = t >> 6, fr = lane & 15, fq = lane >> 4;
;     char* sK = smem; char* sV = smem + 8192; float* sF = (float*)(smem + 16384);
;     const int qw0 = wid * 32;
;     const bool wave_valid = qw0 < nq;
;     bf16x8 qf[2][2]; int kmax[2]; float fqv[2]; bool rvalid[2];
; #pragma unroll
;     for (int qt = 0; qt < 2; ++qt) {
;         const int qi = qw0 + qt * 16 + fr, qc = min(qi, nq - 1);
; #pragma unroll
;         for (int kk = 0; kk < 2; ++kk) qf[qt][kk] = *(const bf16x8*)(Q + (size_t)qc * ldq + kk * 32 + fq * 8);
;         rvalid[qt] = qi < nq;
;         kmax[qt] = rvalid[qt] ? q_pos0 + qi - (SB ? 1 : 0) : -1;
;         fqv[qt] = SB ? 0.f : Fq[qc] * LOG2E;
;     }
;     const int wave_kmax = wave_valid ? q_pos0 + min(qw0 + 31, nq - 1) - (SB ? 1 : 0) : -1;
;     const int kt_hi = (q_pos0 + nq - 1) >> 6;
;     f32x4 o[4][2];
; #pragma unroll
;     for (int a = 0; a < 4; ++a) { o[a][0] = (f32x4){0.f, 0.f, 0.f, 0.f}; o[a][1] = (f32x4){0.f, 0.f, 0.f, 0.f}; }
;     float m[2] = {-1e30f, -1e30f}, ls[2] = {SB ? 1.f : 0.f, SB ? 1.f : 0.f};
;     const int srow = t >> 2, sch = (t & 3) * 2;
;     uint4 rk0, rk1, rv0, rv1; float rf = 0.f;
;     {
;         const size_t kb = (size_t)kt_hi * 64;
;         const bf16_t* kp = Kp + (kb + srow) * ldk + sch * 8; rk0 = *(const uint4*)kp; rk1 = *(const uint4*)(kp + 8);
;         const bf16_t* vp = VT + (size_t)srow * ldvt + kb + sch * 8; rv0 = *(const uint4*)vp; rv1 = *(const uint4*)(vp + 8);
;         if (!SB && t < 64) rf = Fk[kb + t];
;     }
;     const int so0 = srow * 128 + ((sch ^ (srow & 7)) << 4), so1 = srow * 128 + (((sch + 1) ^ (srow & 7)) << 4);
;     const int sw = fr & 7;
;     volatile int* xflag = (volatile int*)(smem + 16384 + 256);
;     if (t < 4) xflag[t] = 0;
.LBB0_852:
	v_readlane_b32 s13, v250, 53
	s_lshl_b32 s4, s12, 6
	s_ashr_i32 s5, s4, 31
	s_lshl_b64 s[12:13], s[4:5], 1
	s_add_u32 s4, s0, s12
	s_addc_u32 s5, s1, s13
	s_ashr_i32 s23, s22, 31
	s_lshl_b64 s[0:1], s[22:23], 9
	s_add_u32 s0, s29, s0
	s_addc_u32 s1, s30, s1
	s_add_u32 s0, s0, s12
	v_mov_b32_e32 v68, v186
	v_writelane_b32 v250, s12, 40
	s_addc_u32 s1, s1, s13
	s_add_i32 s11, s9, -1
	v_and_b32_e32 v32, 48, v68
	v_ashrrev_i32_e32 v69, 6, v68
	v_lshl_add_u64 v[8:9], s[0:1], 0, v[32:33]
	s_add_i32 s0, s11, s10
	v_and_b32_e32 v70, 15, v68
	v_lshlrev_b32_e32 v71, 5, v69
	s_ashr_i32 s0, s0, 6
	v_or_b32_e32 v98, v71, v70
	v_ashrrev_i32_e32 v100, 2, v68
	s_ashr_i32 s1, s0, 31
	v_writelane_b32 v250, s13, 41
	v_or_b32_e32 v96, 16, v98
	v_lshlrev_b32_e32 v16, 1, v68
	s_lshl_b64 s[12:13], s[0:1], 6
	v_ashrrev_i32_e32 v101, 31, v100
	v_min_i32_e32 v0, s11, v98
	v_min_i32_e32 v10, s11, v96
	v_and_b32_e32 v72, 6, v16
	v_lshl_add_u64 v[16:17], s[12:13], 0, v[100:101]
	v_mad_i64_i32 v[24:25], s[12:13], s8, v100, 0
	v_ashrrev_i32_e32 v1, 31, v0
	v_ashrrev_i32_e32 v11, 31, v10
	v_lshlrev_b64 v[16:17], 9, v[16:17]
	v_lshl_add_u64 v[66:67], v[24:25], 1, s[6:7]
	s_lshl_b64 s[6:7], s[0:1], 7
	v_lshlrev_b64 v[0:1], 9, v[0:1]
	v_lshlrev_b64 v[10:11], 9, v[10:11]
	v_lshl_add_u64 v[16:17], s[4:5], 0, v[16:17]
	v_lshlrev_b32_e32 v32, 4, v72
	v_lshl_add_u64 v[24:25], v[66:67], 0, s[6:7]
	v_lshl_add_u64 v[4:5], v[8:9], 0, v[0:1]
	v_lshl_add_u64 v[12:13], v[8:9], 0, v[10:11]
	v_lshl_add_u64 v[20:21], v[16:17], 0, v[32:33]
	v_lshl_add_u64 v[28:29], v[24:25], 0, v[32:33]
	flat_load_dwordx4 v[0:3], v[4:5]
	s_nop 0
	flat_load_dwordx4 v[4:7], v[4:5] offset:64
	s_nop 0
	flat_load_dwordx4 v[8:11], v[12:13]
	s_nop 0
	flat_load_dwordx4 v[12:15], v[12:13] offset:64
	s_nop 0
	flat_load_dwordx4 v[16:19], v[20:21]
	s_nop 0
	flat_load_dwordx4 v[20:23], v[20:21] offset:16
	s_nop 0
	flat_load_dwordx4 v[24:27], v[28:29]
	s_nop 0
	flat_load_dwordx4 v[28:31], v[28:29] offset:16
	v_cmp_gt_i32_e32 vcc, 4, v68
	s_and_saveexec_b64 s[6:7], vcc
	s_cbranch_execz .LBB0_854
	s_mov_b64 s[12:13], src_shared_base
	v_lshl_add_u32 v32, v68, 2, 0
	v_add_u32_e32 v34, 0x4100, v32
	v_mov_b32_e32 v35, s13
	ds_write_b32 v34, v33
	s_waitcnt vmcnt(0) lgkmcnt(0)

; template <bool SB> ...
;     ...
;         __syncthreads();
;         if (early && (xflag[0] & xflag[1] & xflag[2] & xflag[3])) break;
;         *(uint4*)(sK + so0) = rk0; *(uint4*)(sK + so1) = rk1; *(uint4*)(sV + so0) = rv0; *(uint4*)(sV + so1) = rv1;
;         if (!SB && t < 64) sF[t] = rf * LOG2E;
;         __syncthreads();
;         if (kt > 0) {
;             const size_t kb = (size_t)(kt - 1) * 64;
;             const bf16_t* kp = Kp + (kb + srow) * ldk + sch * 8; rk0 = *(const uint4*)kp; rk1 = *(const uint4*)(kp + 8);
;             const bf16_t* vp = VT + (size_t)srow * ldvt + kb + sch * 8; rv0 = *(const uint4*)vp; rv1 = *(const uint4*)(vp + 8);
;             if (!SB && t < 64) rf = Fk[kb + t];
;         }
.LBB0_860:
	v_mov_b32_e32 v66, 0x4100
	s_waitcnt vmcnt(0) lgkmcnt(0)
	s_barrier
	ds_read_b128 v[66:69], v66
	s_or_b64 s[34:35], s[34:35], exec
	s_waitcnt lgkmcnt(0)
	v_and_b32_e32 v68, v66, v68
	v_bitop3_b32 v66, v68, v67, v69 bitop3:0x80
	v_cmp_eq_u32_e32 vcc, 0, v66
	s_and_saveexec_b64 s[38:39], vcc
	s_cbranch_execz .LBB0_859
	v_readlane_b32 s92, v252, 27
	v_readlane_b32 s93, v252, 28
	s_cmp_eq_u32 s92, -1
	ds_write_b128 v173, v[16:19]
	ds_write_b128 v174, v[20:23]
	ds_write_b128 v173, v[24:27] offset:8192
	ds_write_b128 v174, v[28:31] offset:8192
	s_waitcnt lgkmcnt(0)
	s_barrier
	s_cbranch_scc1 .LBB0_863
	s_lshl_b64 s[0:1], s[92:93], 6
	v_lshl_add_u64 v[16:17], s[0:1], 0, v[100:101]
	v_lshlrev_b64 v[16:17], 9, v[16:17]
	s_lshl_b64 s[0:1], s[92:93], 7
	v_lshl_add_u64 v[20:21], v[102:103], 0, v[16:17]
	v_lshl_add_u64 v[28:29], v[104:105], 0, s[0:1]
	flat_load_dwordx4 v[16:19], v[20:21]
	s_nop 0
	flat_load_dwordx4 v[20:23], v[20:21] offset:16
	s_nop 0
	flat_load_dwordx4 v[24:27], v[28:29]
	s_nop 0
	flat_load_dwordx4 v[28:31], v[28:29] offset:16

; template <bool SB> ...
;     ...
;         if (early) {
;             int pred;
;             if (!SB) {
;                 const float f0 = sF[0];
;                 pred = (!rvalid[0] || (qkb * LOG2E + fqv[0] - f0 < m[0] - 104.f * LOG2E)) && (!rvalid[1] || (qkb * LOG2E + fqv[1] - f0 < m[1] - 104.f * LOG2E));
;             } else {
;                 pred = (!rvalid[0] || ls[0] == 0.f) && (!rvalid[1] || ls[1] == 0.f);
;             }
;             const int wall = __all(pred);
;             if (lane == 0) xflag[wid] = wall;
;         }
.LBB0_865:
	s_or_b64 exec, exec, s[54:55]
	v_cmp_eq_f32_e32 vcc, 0, v109
	s_or_b64 s[0:1], s[14:15], vcc
	v_cmp_eq_f32_e32 vcc, 0, v108
	s_or_b64 s[4:5], s[12:13], vcc
	s_and_b64 s[0:1], s[0:1], s[4:5]
	v_cndmask_b32_e64 v66, 0, 1, s[0:1]
	v_cmp_ne_u32_e32 vcc, 0, v66
	s_mov_b64 s[0:1], exec
	s_and_saveexec_b64 s[4:5], s[40:41]
	s_cbranch_execz .LBB0_858
	s_cmp_eq_u64 vcc, s[0:1]
	s_cselect_b64 s[0:1], -1, 0
	v_cndmask_b32_e64 v66, 0, 1, s[0:1]
	ds_write_b32 v106, v66
	s_waitcnt lgkmcnt(0)
	s_branch .LBB0_858

; template <bool SB> ...
;     ...
;     const int srow = t >> 2, sch = (t & 3) * 2;
;     uint4 rk0, rk1, rv0, rv1; float rf = 0.f;
;     {
;         const size_t kb = (size_t)kt_hi * 64;
;         const bf16_t* kp = Kp + (kb + srow) * ldk + sch * 8; rk0 = *(const uint4*)kp; rk1 = *(const uint4*)(kp + 8);
;         const bf16_t* vp = VT + (size_t)srow * ldvt + kb + sch * 8; rv0 = *(const uint4*)vp; rv1 = *(const uint4*)(vp + 8);
;         if (!SB && t < 64) rf = Fk[kb + t];
;     }
;     const int so0 = srow * 128 + ((sch ^ (srow & 7)) << 4), so1 = srow * 128 + (((sch + 1) ^ (srow & 7)) << 4);
;     const int sw = fr & 7;
;     volatile int* xflag = (volatile int*)(smem + 16384 + 256);
;     if (t < 4) xflag[t] = 0;
.LBB0_891:
	s_or_b64 exec, exec, s[8:9]
	v_cmp_gt_i32_e32 vcc, 4, v0
	v_lshl_add_u32 v171, v0, 2, 0
	s_and_saveexec_b64 s[8:9], vcc
	s_cbranch_execz .LBB0_893
	s_mov_b64 s[16:17], src_shared_base
	v_add_u32_e32 v12, 0x4100, v171
	v_mov_b32_e32 v13, s17
	ds_write_b32 v12, v33
	s_waitcnt vmcnt(0) lgkmcnt(0)

; template <bool SB> ...
;     ...
;         __syncthreads();
;         if (early && (xflag[0] & xflag[1] & xflag[2] & xflag[3])) break;
;         *(uint4*)(sK + so0) = rk0; *(uint4*)(sK + so1) = rk1; *(uint4*)(sV + so0) = rv0; *(uint4*)(sV + so1) = rv1;
;         if (!SB && t < 64) sF[t] = rf * LOG2E;
;         __syncthreads();
.LBB0_900:
	v_cndmask_b32_e64 v0, 0, 1, s[26:27]
	v_cmp_ne_u32_e64 s[48:49], 1, v0
	s_andn2_b64 vcc, exec, s[26:27]
	s_mov_b64 s[16:17], s[58:59]
	s_barrier
	s_cbranch_vccnz .LBB0_902
	v_mov_b32_e32 v0, 0x4100
	ds_read_b128 v[0:3], v0
	s_andn2_b64 s[0:1], s[58:59], exec
	s_waitcnt lgkmcnt(0)
	v_and_b32_e32 v2, v0, v2
	v_bitop3_b32 v0, v2, v1, v3 bitop3:0x80
	v_cmp_eq_u32_e32 vcc, 0, v0
	s_and_b64 s[14:15], vcc, exec
	s_or_b64 s[16:17], s[0:1], s[14:15]

; template <bool SB> ...
;     ...
;         if (early) {
;             int pred;
;             if (!SB) {
;                 const float f0 = sF[0];
;                 pred = (!rvalid[0] || (qkb * LOG2E + fqv[0] - f0 < m[0] - 104.f * LOG2E)) && (!rvalid[1] || (qkb * LOG2E + fqv[1] - f0 < m[1] - 104.f * LOG2E));
;             } else {
;                 pred = (!rvalid[0] || ls[0] == 0.f) && (!rvalid[1] || ls[1] == 0.f);
;             }
;             const int wall = __all(pred);
;             if (lane == 0) xflag[wid] = wall;
;         }
.LBB0_930:
	s_or_b64 exec, exec, s[16:17]
	v_cndmask_b32_e64 v0, 0, 1, s[0:1]
	s_mov_b64 s[16:17], exec
	v_cmp_ne_u32_e32 vcc, 0, v0
	s_and_saveexec_b64 s[0:1], s[46:47]
	s_cbranch_execz .LBB0_897
	s_cmp_eq_u64 vcc, s[16:17]
	s_cselect_b64 s[16:17], -1, 0
	v_cndmask_b32_e64 v0, 0, 1, s[16:17]
	ds_write_b32 v166, v0
	s_waitcnt lgkmcnt(0)
	s_branch .LBB0_897

; __global__ void __launch_bounds__(256, 2) fwd_kernel(Params p) {
;     ...
;                 for (int tile = bid; tile < MT * 11; tile += nb) {
;                     int mt, nt;
;                     if (tile < 128 * 11) { const int x = tile & 7, q = tile >> 3, g = q >> 6, r = q & 63; mt = (r & 15) * 8 + x; nt = g * 4 + (r >> 4); } else { mt = 128; nt = tile - 128 * 11; }
;                     gemm1_big(pq, l, mt, nt, smem);
.LBB0_1937:
	s_andn2_b64 vcc, exec, s[22:23]
	s_movk_i32 s28, 0x80
	s_cbranch_vccnz .LBB0_1939
	s_ashr_i32 s1, s74, 7
	s_bfe_u32 s0, s74, 0x20007
	s_and_b32 s1, s1, -4
	s_and_b32 s28, s74, 0x7f
	s_or_b32 s0, s1, s0
	s_sub_i32 s1, 18, s0
	s_cmp_ge_i32 s0, 8
	s_cselect_b32 s0, s1, s0

;     __device__ __forceinline__ bf16_t* Wf1() const { return (bf16_t*)(ws + OFF_Wf1); }
;     __device__ __forceinline__ bf16_t* Wf2() const { return (bf16_t*)(ws + OFF_Wf2); }
; DEV WtDesc wt_desc(const Params& p, int job) {
;     ...
;     } else if ((j -= 256) < 1408) {
;         const int tn = j / 16, tk = j % 16;
;         src = p.w_ffn_in + (size_t)l * 1024 * 5632 + (size_t)tk * 64 * 5632; ld = 5632; ca = tn * 32; cb = DFF + tn * 32;
;         dst = p.Wf1() + (size_t)l * 5632 * 1024 + (size_t)tn * 64 * 1024 + tk * 64; ldd = 1024;
;     } else {
;         j -= 1408; const int tn = j / 44, tk = j % 44;
;         src = p.w_ffn_out + (size_t)l * DFF * 1024 + (size_t)tk * 64 * 1024; ld = 1024; ca = tn * 64; cb = ca + 32;
;         dst = p.Wf2() + (size_t)l * 1024 * DFF + (size_t)tn * 64 * DFF + tk * 64; ldd = DFF;
;     }
;     WtDesc d; d.src = src; d.dst = dst; d.ld = ld; d.ca = ca; d.cb = cb; d.ldd = ldd; return d;
.LBB0_2645:
	s_cmpk_gt_i32 s78, 0x1fbf
	s_cbranch_scc1 .LBB0_2706
	s_mul_hi_i32 s0, s78, 0x81020409
	s_add_i32 s0, s0, s78
	s_lshr_b32 s1, s0, 31
	s_ashr_i32 s0, s0, 11
	s_add_i32 s2, s0, s1
	s_mul_i32 s0, s2, 0xfe0
	s_sub_i32 s10, s78, s0
	s_cmpk_gt_i32 s10, 0x59f
	s_mov_b64 s[8:9], -1
	s_cbranch_scc0 .LBB0_2667
	s_cmpk_gt_u32 s10, 0x5ff
	s_cbranch_scc0 .LBB0_2664
	s_cmpk_gt_u32 s10, 0x65f
	s_cbranch_scc0 .LBB0_2661
	s_cmpk_gt_u32 s10, 0x69f
	s_cbranch_scc0 .LBB0_2658
	s_cmpk_gt_u32 s10, 0x79f
	s_cbranch_scc0 .LBB0_2655
	s_mov_b64 s[6:7], -1
	s_cmpk_gt_u32 s10, 0xd1f
	s_mul_hi_i32 s3, s2, 0xb00000
	s_mul_i32 s8, s2, 0xb00000
	s_cbranch_scc0 .LBB0_2653
	s_add_i32 s0, s10, 0xf2e0
	s_and_b32 s1, s0, 0xffff
	s_mul_i32 s1, s1, 0xba2f
	s_lshr_b32 s6, s1, 21
	s_mul_i32 s1, s6, 44
	s_sub_i32 s0, s0, s1
	s_and_b32 s7, s0, 0xffff
	v_readlane_b32 s4, v253, 63
	v_readlane_b32 s12, v252, 27
	v_readlane_b32 s5, v254, 0
	s_add_u32 s4, s4, s8
	v_readlane_b32 s13, v252, 28
	s_addc_u32 s5, s5, s3
	s_mov_b32 s1, s13
	s_lshl_b32 s0, s0, 16
	s_lshl_b64 s[0:1], s[0:1], 2
	s_add_u32 s4, s4, s0
	s_addc_u32 s5, s5, s1
	s_lshl_b32 s11, s6, 6
	s_mov_b32 s9, s13
	s_or_b32 s13, s11, 32
	s_mul_i32 s1, s2, 0x580000
	v_readlane_b32 s14, v254, 1
	s_mul_hi_i32 s0, s2, 0x580000
	v_readlane_b32 s15, v254, 2
	s_add_u32 s1, s14, s1
	s_addc_u32 s0, s15, s0
	s_mul_i32 s6, s6, 0x58000
	s_add_u32 s1, s1, s6
	s_addc_u32 s0, s0, 0
	s_lshl_b32 s6, s7, 8
	s_add_u32 s1, s1, s6
	s_addc_u32 s6, s0, 0
	v_writelane_b32 v252, s8, 27
	s_add_u32 s0, s1, 0x3500001
	s_addc_u32 s1, s6, 0
	v_writelane_b32 v252, s9, 28
	s_mov_b64 s[6:7], 0

; DEV int tid_opaque() { int t = threadIdx.x; asm volatile("" : "+v"(t)); return t; }
; DEV unsigned pk_bf16(float lo, float hi) { const f32x2_t f = {lo, hi}; const bf16x2_t b = __builtin_convertvector(f, bf16x2_t); return __builtin_bit_cast(unsigned, b); }
; DEV void wt_store(const WtDesc& d, const float (&r)[16], float* sm) {
;     const int t = tid_opaque(), c = t & 63, r0 = t >> 6;
; #pragma unroll
;     for (int i = 0; i < 16; ++i) sm[(r0 + 4 * i) * 65 + c] = r[i];
;     __syncthreads();
;     const int n = t >> 2, kc = (t & 3) * 16;
;     unsigned w[8];
; #pragma unroll
;     for (int e = 0; e < 8; ++e) w[e] = pk_bf16(sm[(kc + 2 * e) * 65 + n], sm[(kc + 2 * e + 1) * 65 + n]);
;     uint4* o = (uint4*)(d.dst + (size_t)n * d.ldd + kc);
;     o[0] = make_uint4(w[0], w[1], w[2], w[3]);
;     o[1] = make_uint4(w[4], w[5], w[6], w[7]);
;     __syncthreads();
; }
.LBB0_2676:
	v_mov_b32_e32 v32, v186
	v_readlane_b32 s6, v254, 4
	v_and_b32_e32 v34, 63, v32
	v_ashrrev_i32_e32 v35, 6, v32
	v_lshlrev_b32_e32 v34, 2, v34
	v_mul_lo_u32 v35, v35, s4
	v_add3_u32 v34, 0, v34, v35
	s_waitcnt vmcnt(0) lgkmcnt(0)
	ds_write_b32 v34, v0
	ds_write_b32 v34, v1 offset:1040
	ds_write_b32 v34, v2 offset:2080
	ds_write_b32 v34, v3 offset:3120
	ds_write_b32 v34, v4 offset:4160
	ds_write_b32 v34, v5 offset:5200
	ds_write_b32 v34, v6 offset:6240
	ds_write_b32 v34, v7 offset:7280
	ds_write_b32 v34, v8 offset:8320
	ds_write_b32 v34, v9 offset:9360
	ds_write_b32 v34, v10 offset:10400
	ds_write_b32 v34, v11 offset:11440
	ds_write_b32 v34, v12 offset:12480
	ds_write_b32 v34, v13 offset:13520
	ds_write_b32 v34, v14 offset:14560
	ds_write_b32 v34, v15 offset:15600
	v_lshlrev_b32_e32 v0, 4, v32
	v_and_b32_e32 v14, 48, v0
	v_mul_u32_u24_e32 v0, 0x41, v14
	v_and_b32_e32 v2, -4, v32
	v_lshlrev_b32_e32 v3, 2, v0
	v_add3_u32 v10, 0, v2, v3
	v_add3_u32 v12, 0, v3, v2
	s_waitcnt lgkmcnt(0)
	s_barrier
	ds_read2_b32 v[0:1], v10 offset1:130
	ds_read2_b32 v[2:3], v12 offset0:65 offset1:195
	v_add_u32_e32 v4, 0x400, v12
	v_add_u32_e32 v6, 0x800, v10
	v_add_u32_e32 v8, 0x800, v12
	ds_read2_b32 v[4:5], v4 offset0:69 offset1:199
	s_waitcnt lgkmcnt(1)
	v_cvt_pk_bf16_f32 v0, v0, v2
	v_add_u32_e32 v2, 0x400, v10
	v_cvt_pk_bf16_f32 v1, v1, v3
	ds_read2_b32 v[2:3], v2 offset0:4 offset1:134
	ds_read2_b32 v[6:7], v6 offset0:8 offset1:138
	ds_read2_b32 v[8:9], v8 offset0:73 offset1:203
	v_add_u32_e32 v10, 0xc00, v10
	v_add_u32_e32 v12, 0xc00, v12
	ds_read2_b32 v[10:11], v10 offset0:12 offset1:142
	ds_read2_b32 v[12:13], v12 offset0:77 offset1:207
	v_readlane_b32 s7, v254, 5
	v_ashrrev_i32_e32 v15, 2, v32
	s_mov_b32 s8, s6
	s_add_i32 s30, s30, s6
	s_waitcnt lgkmcnt(4)
	v_cvt_pk_bf16_f32 v2, v2, v4
	v_cvt_pk_bf16_f32 v3, v3, v5
	s_waitcnt lgkmcnt(2)
	v_cvt_pk_bf16_f32 v4, v6, v8
	v_cvt_pk_bf16_f32 v5, v7, v9
	v_mad_u64_u32 v[8:9], s[6:7], v15, s12, 0
	s_waitcnt lgkmcnt(0)
	v_cvt_pk_bf16_f32 v6, v10, v12
	v_cvt_pk_bf16_f32 v7, v11, v13
	v_ashrrev_i32_e32 v11, 31, v15
	v_mov_b32_e32 v10, v9
	v_mad_u64_u32 v[10:11], s[6:7], v11, s12, v[10:11]
	v_mov_b32_e32 v9, v10
	v_lshl_add_u64 v[8:9], v[8:9], 1, s[0:1]
	v_lshlrev_b32_e32 v32, 1, v14
	v_lshl_add_u64 v[8:9], v[8:9], 0, v[32:33]
	s_add_i32 s29, s29, s8
	s_bitcmp1_b32 s0, 0
	s_cbranch_scc0 .Lwt_lin
	s_and_b32 s0, s0, -2
	s_lshl_b32 s6, s12, 2
	v_lshrrev_b32_e32 v10, 3, v186
	v_mul_u32_u24_e32 v10, s6, v10
	v_and_b32_e32 v11, 2, v186
	v_lshl_or_b32 v10, v11, 6, v10
	v_and_b32_e32 v11, 4, v186
	v_lshl_or_b32 v10, v11, 4, v10
	v_and_b32_e32 v11, 1, v186
	v_lshl_or_b32 v10, v11, 5, v10
	v_mov_b32_e32 v11, 0
	v_lshl_add_u64 v[8:9], s[0:1], 0, v[10:11]

;     __device__ __forceinline__ bf16_t* Wf1() const { return (bf16_t*)(ws + OFF_Wf1); }
;     __device__ __forceinline__ bf16_t* Wf2() const { return (bf16_t*)(ws + OFF_Wf2); }
; DEV WtDesc wt_desc(const Params& p, int job) {
;     ...
;     } else if ((j -= 256) < 1408) {
;         const int tn = j / 16, tk = j % 16;
;         src = p.w_ffn_in + (size_t)l * 1024 * 5632 + (size_t)tk * 64 * 5632; ld = 5632; ca = tn * 32; cb = DFF + tn * 32;
;         dst = p.Wf1() + (size_t)l * 5632 * 1024 + (size_t)tn * 64 * 1024 + tk * 64; ldd = 1024;
;     } else {
;         j -= 1408; const int tn = j / 44, tk = j % 44;
;         src = p.w_ffn_out + (size_t)l * DFF * 1024 + (size_t)tk * 64 * 1024; ld = 1024; ca = tn * 64; cb = ca + 32;
;         dst = p.Wf2() + (size_t)l * 1024 * DFF + (size_t)tn * 64 * DFF + tk * 64; ldd = DFF;
;     }
;     WtDesc d; d.src = src; d.dst = dst; d.ld = ld; d.ca = ca; d.cb = cb; d.ldd = ldd; return d;
; DEV void wt_all(const Params& p, int bid, int nb, float* sm) {
;     ...
;     for (;;) {
;         const int nj = job + nb; const bool more = nj < 2 * WT_JOBS_L;
;         WtDesc dn = d; float rn[16];
;         if (more) { dn = wt_desc(p, nj); wt_load(dn, rn); }
;         wt_store(d, r, sm);
;         if (!more) break;
;         d = dn; job = nj;
.LBB0_2677:
	s_cmpk_gt_i32 s29, 0x1fbf
	s_cbranch_scc1 .LBB0_2676
	s_mul_hi_i32 s2, s29, 0x81020409
	s_add_i32 s2, s2, s29
	s_lshr_b32 s3, s2, 31
	s_ashr_i32 s2, s2, 11
	s_add_i32 s4, s2, s3
	s_mul_i32 s2, s4, 0xfffff020
	s_add_i32 s31, s29, s2
	s_cmpk_gt_i32 s31, 0x59f
	s_mov_b64 s[10:11], -1
	s_cbranch_scc0 .LBB0_2699
	s_cmpk_gt_u32 s31, 0x5ff
	s_cbranch_scc0 .LBB0_2696
	s_cmpk_gt_u32 s31, 0x65f
	s_cbranch_scc0 .LBB0_2693
	s_cmpk_gt_u32 s31, 0x69f
	s_cbranch_scc0 .LBB0_2690
	s_cmpk_gt_u32 s31, 0x79f
	s_cbranch_scc0 .LBB0_2687
	s_mov_b64 s[8:9], -1
	s_cmpk_gt_u32 s31, 0xd1f
	s_mul_hi_i32 s5, s4, 0xb00000
	s_mul_i32 s10, s4, 0xb00000
	s_cbranch_scc0 .LBB0_2685
	s_add_i32 s2, s31, 0xf2e0
	s_and_b32 s3, s2, 0xffff
	s_mul_i32 s3, s3, 0xba2f
	s_lshr_b32 s8, s3, 21
	s_mul_i32 s3, s8, 44
	s_sub_i32 s2, s2, s3
	s_and_b32 s9, s2, 0xffff
	v_readlane_b32 s6, v253, 63
	v_readlane_b32 s34, v252, 27
	v_readlane_b32 s7, v254, 0
	s_add_u32 s6, s6, s10
	v_readlane_b32 s35, v252, 28
	s_addc_u32 s7, s7, s5
	s_mov_b32 s3, s35
	s_lshl_b32 s2, s2, 16
	s_lshl_b64 s[2:3], s[2:3], 2
	s_add_u32 s6, s6, s2
	s_addc_u32 s7, s7, s3
	s_lshl_b32 s34, s8, 6
	s_mov_b32 s11, s35
	s_or_b32 s35, s34, 32
	s_mul_i32 s3, s4, 0x580000
	s_mul_hi_i32 s2, s4, 0x580000
	s_add_u32 s3, s13, s3
	s_addc_u32 s2, s14, s2
	s_mul_i32 s8, s8, 0x58000
	s_add_u32 s3, s3, s8
	s_addc_u32 s8, s2, 0
	s_lshl_b32 s2, s9, 8
	v_writelane_b32 v252, s10, 27
	s_add_u32 s2, s3, s2
	s_addc_u32 s3, s8, 0
	s_or_b32 s2, s2, 1
	v_writelane_b32 v252, s11, 28
	s_mov_b64 s[8:9], 0
